# FFN-out and out-proj residual GEMMs hand-written: 192x128 tiles, one full-K tile per workgroup, no split-K partial (LayerNorm no longer adds one)
# speedup vs baseline: 1.1428x; 1.0209x over previous
.LBB0_46:
	v_add_u32_e32 v80, 0x1000, v144
	v_add_u32_e32 v131, 0x2000, v144
	v_lshrrev_b32_e32 v80, 12, v80
	s_movk_i32 s4, 0xfff
	v_add_u32_e32 v80, 1, v80
	v_cmp_lt_i32_e32 vcc, s4, v131
	v_lshl_add_u64 v[160:161], v[148:149], 0, v[146:147]
	global_load_dwordx4 v[112:115], v[160:161], off
	global_load_dwordx4 v[116:119], v[160:161], off offset:1024
	global_load_dwordx4 v[120:123], v[160:161], off offset:2048
	global_load_dwordx4 v[124:127], v[160:161], off offset:3072
	v_cndmask_b32_e32 v128, 0, v80, vcc
	v_lshl_add_u64 v[80:81], v[128:129], 0, s[56:57]
	v_mad_u64_u32 v[82:83], s[34:35], v80, s84, v[154:155]
	v_mad_i32_i24 v83, v81, s84, v83
	v_lshl_add_u64 v[80:81], v[82:83], 0, v[158:159]
	s_waitcnt vmcnt(4)
	v_add_co_u32_e32 v86, vcc, 0x1000, v80
	v_lshl_add_u64 v[84:85], v[80:81], 0, s[48:49]
	s_nop 0
	v_addc_co_u32_e32 v87, vcc, 0, v81, vcc
	global_load_dwordx4 v[104:107], v[80:81], off
	global_load_dwordx4 v[96:99], v[80:81], off offset:1024
	global_load_dwordx4 v[100:103], v[84:85], off offset:1024
	global_load_dwordx4 v[92:95], v[84:85], off offset:2048
	global_load_dwordx4 v[88:91], v[80:81], off offset:2048
	s_nop 0
	global_load_dwordx4 v[80:83], v[80:81], off offset:3072
	s_nop 0
	global_load_dwordx4 v[108:111], v[86:87], off
	s_nop 0
	global_load_dwordx4 v[84:87], v[84:85], off offset:3072
	s_movk_i32 s4, 0x7fff
	v_cmp_lt_i32_e32 vcc, s4, v131
	s_and_saveexec_b64 s[34:35], vcc
	s_cbranch_execz .LBB0_48
	v_mov_b32_e32 v145, v129
	v_lshlrev_b64 v[162:163], 12, v[144:145]
	v_lshl_add_u64 v[166:167], v[140:141], 0, v[162:163]
	global_load_dwordx4 v[162:165], v[166:167], off
	s_waitcnt vmcnt(0)
	v_pk_add_f32 v[112:113], v[112:113], v[162:163]
	v_pk_add_f32 v[114:115], v[114:115], v[164:165]
	global_load_dwordx4 v[162:165], v[166:167], off offset:1024
	s_waitcnt vmcnt(0)
	v_pk_add_f32 v[116:117], v[116:117], v[162:163]
	v_pk_add_f32 v[118:119], v[118:119], v[164:165]
	global_load_dwordx4 v[162:165], v[166:167], off offset:2048
	s_waitcnt vmcnt(0)
	v_pk_add_f32 v[120:121], v[120:121], v[162:163]
	v_pk_add_f32 v[122:123], v[122:123], v[164:165]
	global_load_dwordx4 v[162:165], v[166:167], off offset:3072
	s_waitcnt vmcnt(0)
	v_pk_add_f32 v[124:125], v[124:125], v[162:163]
	v_pk_add_f32 v[126:127], v[126:127], v[164:165]
.LBB0_48:
	s_or_b64 exec, exec, s[34:35]
	v_readlane_b32 s2, v236, 21
	s_movk_i32 s4, 0x3000
	s_nop 0
	v_add_u32_e32 v164, s2, v144
	v_add_u32_e32 v162, 0x2000, v164
	v_cmp_gt_i32_e64 s[34:35], s4, v162
	v_ashrrev_i32_e32 v163, 31, v162
	s_and_saveexec_b64 s[36:37], s[34:35]
	s_cbranch_execz .LBB0_52
	v_add_u32_e32 v32, 0x1000, v164
	v_lshrrev_b32_e32 v32, 12, v32
	s_movk_i32 s4, 0xfff
	v_add_u32_e32 v32, 1, v32
	v_cmp_lt_i32_e32 vcc, s4, v162
	v_mov_b64_e32 v[50:51], s[54:55]
	v_mov_b32_e32 v157, v129
	v_cndmask_b32_e32 v128, 0, v32, vcc
	v_lshl_add_u64 v[48:49], v[128:129], 0, s[56:57]
	v_mad_u64_u32 v[50:51], s[62:63], v48, s84, v[50:51]
	v_mad_i32_i24 v51, v49, s84, v51
	v_lshl_add_u64 v[56:57], v[50:51], 0, v[156:157]
	v_lshlrev_b64 v[32:33], 12, v[162:163]
	v_add_co_u32_e32 v74, vcc, 0x1000, v56
	v_lshl_add_u64 v[44:45], v[138:139], 0, v[32:33]
	v_lshl_add_u64 v[72:73], v[56:57], 0, s[48:49]
	v_addc_co_u32_e32 v75, vcc, 0, v57, vcc
	global_load_dwordx4 v[32:35], v[44:45], off
	global_load_dwordx4 v[36:39], v[44:45], off offset:1024
	global_load_dwordx4 v[40:43], v[44:45], off offset:2048
	s_nop 0
	global_load_dwordx4 v[44:47], v[44:45], off offset:3072
	s_nop 0
	global_load_dwordx4 v[48:51], v[56:57], off
	global_load_dwordx4 v[52:55], v[56:57], off offset:1024
	global_load_dwordx4 v[64:67], v[72:73], off offset:1024
	global_load_dwordx4 v[68:71], v[72:73], off offset:2048
	global_load_dwordx4 v[60:63], v[56:57], off offset:2048
	s_nop 0
	global_load_dwordx4 v[56:59], v[56:57], off offset:3072
	s_nop 0
	global_load_dwordx4 v[76:79], v[74:75], off
	s_nop 0
	global_load_dwordx4 v[72:75], v[72:73], off offset:3072
	s_movk_i32 s4, 0x7fff
	v_cmp_lt_i32_e32 vcc, s4, v162
	s_and_saveexec_b64 s[62:63], vcc
	s_cbranch_execz .LBB0_51
	v_mov_b32_e32 v165, v129
	v_lshlrev_b64 v[164:165], 12, v[164:165]
	v_lshl_add_u64 v[168:169], v[140:141], 0, v[164:165]
	global_load_dwordx4 v[164:167], v[168:169], off
	s_waitcnt vmcnt(0)
	v_pk_add_f32 v[32:33], v[32:33], v[164:165]
	v_pk_add_f32 v[34:35], v[34:35], v[166:167]
	global_load_dwordx4 v[164:167], v[168:169], off offset:1024
	s_waitcnt vmcnt(0)
	v_pk_add_f32 v[36:37], v[36:37], v[164:165]
	v_pk_add_f32 v[38:39], v[38:39], v[166:167]
	global_load_dwordx4 v[164:167], v[168:169], off offset:2048
	s_waitcnt vmcnt(0)
	v_pk_add_f32 v[40:41], v[40:41], v[164:165]
	v_pk_add_f32 v[42:43], v[42:43], v[166:167]
	global_load_dwordx4 v[164:167], v[168:169], off offset:3072
	s_waitcnt vmcnt(0)
	v_pk_add_f32 v[44:45], v[44:45], v[164:165]
	v_pk_add_f32 v[46:47], v[46:47], v[166:167]

.LBB0_95:
	v_add_u32_e32 v80, 0x1000, v144
	v_add_u32_e32 v131, 0x2000, v144
	v_lshrrev_b32_e32 v80, 12, v80
	s_movk_i32 s4, 0xfff
	v_add_u32_e32 v80, 1, v80
	v_cmp_lt_i32_e32 vcc, s4, v131
	v_mov_b64_e32 v[82:83], s[46:47]
	global_load_dwordx4 v[112:115], v[148:149], off offset:-2048
	global_load_dwordx4 v[108:111], v[148:149], off offset:-1024
	global_load_dwordx4 v[104:107], v[148:149], off
	global_load_dwordx4 v[100:103], v[148:149], off offset:1024
	v_cndmask_b32_e32 v128, 0, v80, vcc
	v_lshl_add_u64 v[80:81], v[128:129], 0, s[44:45]
	v_mad_u64_u32 v[82:83], s[34:35], v80, s84, v[82:83]
	v_mad_i32_i24 v83, v81, s84, v83
	v_lshlrev_b32_e32 v128, 2, v136
	v_lshl_add_u64 v[80:81], v[82:83], 0, v[128:129]
	s_waitcnt vmcnt(12)
	v_add_co_u32_e32 v86, vcc, 0x1000, v80
	v_lshl_add_u64 v[84:85], v[80:81], 0, s[48:49]
	s_nop 0
	v_addc_co_u32_e32 v87, vcc, 0, v81, vcc
	global_load_dwordx4 v[96:99], v[80:81], off
	global_load_dwordx4 v[92:95], v[80:81], off offset:1024
	global_load_dwordx4 v[120:123], v[84:85], off offset:1024
	global_load_dwordx4 v[116:119], v[84:85], off offset:2048
	global_load_dwordx4 v[88:91], v[80:81], off offset:2048
	s_nop 0
	global_load_dwordx4 v[80:83], v[80:81], off offset:3072
	s_nop 0
	global_load_dwordx4 v[124:127], v[86:87], off
	s_nop 0
	global_load_dwordx4 v[84:87], v[84:85], off offset:3072
	s_movk_i32 s4, 0x7fff
	v_cmp_lt_i32_e32 vcc, s4, v131
	s_and_saveexec_b64 s[34:35], vcc
	s_cbranch_execz .LBB0_97
	v_mov_b32_e32 v145, v129
	v_lshlrev_b64 v[150:151], 12, v[144:145]
	v_lshl_add_u64 v[154:155], v[140:141], 0, v[150:151]
	global_load_dwordx4 v[150:153], v[154:155], off
	s_waitcnt vmcnt(0)
	v_pk_add_f32 v[112:113], v[112:113], v[150:151]
	v_pk_add_f32 v[114:115], v[114:115], v[152:153]
	global_load_dwordx4 v[150:153], v[154:155], off offset:1024
	s_waitcnt vmcnt(0)
	v_pk_add_f32 v[108:109], v[108:109], v[150:151]
	v_pk_add_f32 v[110:111], v[110:111], v[152:153]
	global_load_dwordx4 v[150:153], v[154:155], off offset:2048
	s_waitcnt vmcnt(0)
	v_pk_add_f32 v[104:105], v[104:105], v[150:151]
	v_pk_add_f32 v[106:107], v[106:107], v[152:153]
	global_load_dwordx4 v[150:153], v[154:155], off offset:3072
	s_waitcnt vmcnt(0)
	v_pk_add_f32 v[100:101], v[100:101], v[150:151]
	v_pk_add_f32 v[102:103], v[102:103], v[152:153]
.LBB0_97:
	s_or_b64 exec, exec, s[34:35]
	v_readlane_b32 s2, v236, 21
	s_movk_i32 s4, 0x3000
	s_nop 0
	v_add_u32_e32 v152, s2, v144
	v_add_u32_e32 v150, 0x2000, v152
	v_cmp_gt_i32_e64 s[34:35], s4, v150
	v_ashrrev_i32_e32 v151, 31, v150
	s_and_saveexec_b64 s[52:53], s[34:35]
	s_cbranch_execz .LBB0_101
	v_add_u32_e32 v32, 0x1000, v152
	v_lshrrev_b32_e32 v32, 12, v32
	s_movk_i32 s4, 0xfff
	v_add_u32_e32 v32, 1, v32
	v_cmp_lt_i32_e32 vcc, s4, v150
	v_mov_b32_e32 v33, v129
	v_mov_b64_e32 v[50:51], s[46:47]
	v_cndmask_b32_e32 v32, 0, v32, vcc
	v_lshl_add_u64 v[48:49], v[32:33], 0, s[44:45]
	v_mad_u64_u32 v[50:51], s[54:55], v48, s84, v[50:51]
	v_mad_i32_i24 v51, v49, s84, v51
	v_lshl_add_u64 v[56:57], v[50:51], 0, v[128:129]
	v_lshlrev_b64 v[32:33], 12, v[150:151]
	v_add_co_u32_e32 v74, vcc, 0x1000, v56
	v_lshl_add_u64 v[44:45], v[138:139], 0, v[32:33]
	v_lshl_add_u64 v[72:73], v[56:57], 0, s[48:49]
	v_addc_co_u32_e32 v75, vcc, 0, v57, vcc
	global_load_dwordx4 v[32:35], v[44:45], off
	global_load_dwordx4 v[36:39], v[44:45], off offset:1024
	global_load_dwordx4 v[40:43], v[44:45], off offset:2048
	s_nop 0
	global_load_dwordx4 v[44:47], v[44:45], off offset:3072
	s_nop 0
	global_load_dwordx4 v[48:51], v[56:57], off
	global_load_dwordx4 v[52:55], v[56:57], off offset:1024
	global_load_dwordx4 v[64:67], v[72:73], off offset:1024
	global_load_dwordx4 v[68:71], v[72:73], off offset:2048
	global_load_dwordx4 v[60:63], v[56:57], off offset:2048
	s_nop 0
	global_load_dwordx4 v[56:59], v[56:57], off offset:3072
	s_nop 0
	global_load_dwordx4 v[76:79], v[74:75], off
	s_nop 0
	global_load_dwordx4 v[72:75], v[72:73], off offset:3072
	s_movk_i32 s4, 0x7fff
	v_cmp_lt_i32_e32 vcc, s4, v150
	s_and_saveexec_b64 s[54:55], vcc
	s_cbranch_execz .LBB0_100
	v_mov_b32_e32 v153, v129
	v_lshlrev_b64 v[152:153], 12, v[152:153]
	v_lshl_add_u64 v[156:157], v[140:141], 0, v[152:153]
	global_load_dwordx4 v[152:155], v[156:157], off
	s_waitcnt vmcnt(0)
	v_pk_add_f32 v[32:33], v[32:33], v[152:153]
	v_pk_add_f32 v[34:35], v[34:35], v[154:155]
	global_load_dwordx4 v[152:155], v[156:157], off offset:1024
	s_waitcnt vmcnt(0)
	v_pk_add_f32 v[36:37], v[36:37], v[152:153]
	v_pk_add_f32 v[38:39], v[38:39], v[154:155]
	global_load_dwordx4 v[152:155], v[156:157], off offset:2048
	s_waitcnt vmcnt(0)
	v_pk_add_f32 v[40:41], v[40:41], v[152:153]
	v_pk_add_f32 v[42:43], v[42:43], v[154:155]
	global_load_dwordx4 v[152:155], v[156:157], off offset:3072
	s_waitcnt vmcnt(0)
	v_pk_add_f32 v[44:45], v[44:45], v[152:153]
	v_pk_add_f32 v[46:47], v[46:47], v[154:155]

.Lop_entry:
	v_readlane_b32 s4, v235, 34
	v_readlane_b32 s5, v235, 35
	v_readlane_b32 s55, v235, 44
	s_mul_i32 s53, s55, 0x220000
	s_add_u32 s53, s53, 0xa738000
	s_add_u32 s44, s4, s53
	s_addc_u32 s45, s5, 0
	s_mul_i32 s53, s55, 0x1b000
	s_add_u32 s53, s53, 0xb0fd000
	s_add_u32 s46, s4, s53
	s_addc_u32 s47, s5, 0
	v_and_b32_e32 v225, 63, v170
	v_lshrrev_b32_e32 v226, 6, v170
	v_lshrrev_b32_e32 v227, 1, v226
	v_and_b32_e32 v228, 1, v226
	v_and_b32_e32 v229, 15, v225
	v_lshrrev_b32_e32 v230, 4, v225
	v_lshlrev_b32_e32 v231, 10, v226
	v_lshrrev_b32_e32 v232, 3, v170
	v_readfirstlane_b32 s52, v231
	v_and_b32_e32 v233, 7, v170
	v_bfe_u32 v224, v232, 1, 3
	v_xor_b32_e32 v233, v233, v224
	v_lshlrev_b32_e32 v233, 4, v233
	s_movk_i32 s4, 0x880
	v_mad_u32_u24 v224, v232, s4, v233
	v_and_b32_e32 v233, 15, v232
	v_lshlrev_b32_e32 v233, 1, v233
	v_lshrrev_b32_e32 v168, 4, v232
	v_add_u32_e32 v233, v233, v168
	v_and_b32_e32 v168, 7, v170
	v_bfe_u32 v169, v232, 1, 3
	v_xor_b32_e32 v168, v168, v169
	v_lshlrev_b32_e32 v168, 4, v168
	v_mad_u32_u24 v168, v233, s4, v168
	v_bfe_u32 v233, v229, 1, 3
	v_xor_b32_e32 v231, v230, v233
	v_or_b32_e32 v232, 4, v230
	v_xor_b32_e32 v232, v232, v233
	v_lshlrev_b32_e32 v231, 4, v231
	v_lshlrev_b32_e32 v232, 4, v232
	s_movk_i32 s4, 96
	v_mad_u32_u24 v233, v227, s4, v229
	v_lshlrev_b32_e32 v233, 7, v233
	v_add_u32_e32 v220, v233, v231
	v_add_u32_e32 v221, v233, v232
	v_lshl_add_u32 v233, v228, 6, v229
	v_lshlrev_b32_e32 v233, 7, v233
	v_add_u32_e32 v233, 0x8000, v233
	v_add_u32_e32 v222, v233, v231
	v_add_u32_e32 v223, v233, v232
	v_lshlrev_b32_e32 v231, 2, v230
	v_mad_u32_u24 v231, v227, s4, v231
	v_lshlrev_b32_e32 v232, 5, v228
	v_add_u32_e32 v232, v232, v229
	v_lshlrev_b32_e32 v232, 1, v232
	v_lshlrev_b32_e32 v169, 2, v232
	v_lshl_add_u32 v225, v231, 12, v169
	v_readlane_b32 s54, v237, 0
	s_cmp_ge_u32 s54, 0x200
	s_cbranch_scc1 .Lop_done
	s_add_u32 s57, s52, 0x8000
	s_and_b32 s55, s54, 7
	s_lshl_b32 s55, s55, 3
	s_lshr_b32 s62, s54, 6
	s_add_u32 s55, s55, s62
	s_bfe_u32 s36, s54, 0x30003
	s_lshl_b32 s62, s55, 8
	s_lshl_b32 s63, s36, 4
	s_or_b32 s62, s62, s63
	v_readlane_b32 s4, v235, 34
	v_readlane_b32 s5, v235, 35
	s_mul_i32 s34, s55, 0x66000
	s_add_u32 s34, s34, 0x19ce6000
	s_add_u32 s34, s34, s4
	s_addc_u32 s35, s5, 0
	s_mul_i32 s36, s36, 0x44000
	s_add_u32 s36, s36, s44
	s_addc_u32 s37, s45, 0
	s_add_u32 m0, s52, 0x0
	s_add_u32 s4, s34, 0x0
	s_addc_u32 s5, s35, 0
	global_load_lds_dwordx4 v224, s[4:5]
	s_add_u32 m0, s52, 0x1000
	s_add_u32 s4, s34, 0x11000
	s_addc_u32 s5, s35, 0
	global_load_lds_dwordx4 v224, s[4:5]
	s_add_u32 m0, s52, 0x2000
	s_add_u32 s4, s34, 0x22000
	s_addc_u32 s5, s35, 0
	global_load_lds_dwordx4 v224, s[4:5]
	s_add_u32 m0, s52, 0x3000
	s_add_u32 s4, s34, 0x33000
	s_addc_u32 s5, s35, 0
	global_load_lds_dwordx4 v224, s[4:5]
	s_add_u32 m0, s52, 0x4000
	s_add_u32 s4, s34, 0x44000
	s_addc_u32 s5, s35, 0
	global_load_lds_dwordx4 v224, s[4:5]
	s_add_u32 m0, s52, 0x5000
	s_add_u32 s4, s34, 0x55000
	s_addc_u32 s5, s35, 0
	global_load_lds_dwordx4 v224, s[4:5]
	s_add_u32 m0, s57, 0x0
	s_add_u32 s4, s36, 0x0
	s_addc_u32 s5, s37, 0
	global_load_lds_dwordx4 v168, s[4:5]
	s_add_u32 m0, s57, 0x1000
	s_add_u32 s4, s36, 0x11000
	s_addc_u32 s5, s37, 0
	global_load_lds_dwordx4 v168, s[4:5]
	s_add_u32 m0, s57, 0x2000
	s_add_u32 s4, s36, 0x22000
	s_addc_u32 s5, s37, 0
	global_load_lds_dwordx4 v168, s[4:5]
	s_add_u32 m0, s57, 0x3000
	s_add_u32 s4, s36, 0x33000
	s_addc_u32 s5, s37, 0
	global_load_lds_dwordx4 v168, s[4:5]
	s_add_u32 s36, s36, 0x80
	s_addc_u32 s37, s37, 0
	s_add_u32 s34, s34, 0x80
	s_addc_u32 s35, s35, 0
.Lop_tile:
	s_mov_b32 s56, s62
	v_mov_b32_e32 v0, 0
	v_mov_b32_e32 v1, 0
	v_mov_b32_e32 v2, 0
	v_mov_b32_e32 v3, 0
	v_mov_b32_e32 v4, 0
	v_mov_b32_e32 v5, 0
	v_mov_b32_e32 v6, 0
	v_mov_b32_e32 v7, 0
	v_mov_b32_e32 v8, 0
	v_mov_b32_e32 v9, 0
	v_mov_b32_e32 v10, 0
	v_mov_b32_e32 v11, 0
	v_mov_b32_e32 v12, 0
	v_mov_b32_e32 v13, 0
	v_mov_b32_e32 v14, 0
	v_mov_b32_e32 v15, 0
	v_mov_b32_e32 v16, 0
	v_mov_b32_e32 v17, 0
	v_mov_b32_e32 v18, 0
	v_mov_b32_e32 v19, 0
	v_mov_b32_e32 v20, 0
	v_mov_b32_e32 v21, 0
	v_mov_b32_e32 v22, 0
	v_mov_b32_e32 v23, 0
	v_mov_b32_e32 v24, 0
	v_mov_b32_e32 v25, 0
	v_mov_b32_e32 v26, 0
	v_mov_b32_e32 v27, 0
	v_mov_b32_e32 v28, 0
	v_mov_b32_e32 v29, 0
	v_mov_b32_e32 v30, 0
	v_mov_b32_e32 v31, 0
	v_mov_b32_e32 v32, 0
	v_mov_b32_e32 v33, 0
	v_mov_b32_e32 v34, 0
	v_mov_b32_e32 v35, 0
	v_mov_b32_e32 v36, 0
	v_mov_b32_e32 v37, 0
	v_mov_b32_e32 v38, 0
	v_mov_b32_e32 v39, 0
	v_mov_b32_e32 v40, 0
	v_mov_b32_e32 v41, 0
	v_mov_b32_e32 v42, 0
	v_mov_b32_e32 v43, 0
	v_mov_b32_e32 v44, 0
	v_mov_b32_e32 v45, 0
	v_mov_b32_e32 v46, 0
	v_mov_b32_e32 v47, 0
	v_mov_b32_e32 v48, 0
	v_mov_b32_e32 v49, 0
	v_mov_b32_e32 v50, 0
	v_mov_b32_e32 v51, 0
	v_mov_b32_e32 v52, 0
	v_mov_b32_e32 v53, 0
	v_mov_b32_e32 v54, 0
	v_mov_b32_e32 v55, 0
	v_mov_b32_e32 v56, 0
	v_mov_b32_e32 v57, 0
	v_mov_b32_e32 v58, 0
	v_mov_b32_e32 v59, 0
	v_mov_b32_e32 v60, 0
	v_mov_b32_e32 v61, 0
	v_mov_b32_e32 v62, 0
	v_mov_b32_e32 v63, 0
	v_mov_b32_e32 v64, 0
	v_mov_b32_e32 v65, 0
	v_mov_b32_e32 v66, 0
	v_mov_b32_e32 v67, 0
	v_mov_b32_e32 v68, 0
	v_mov_b32_e32 v69, 0
	v_mov_b32_e32 v70, 0
	v_mov_b32_e32 v71, 0
	v_mov_b32_e32 v72, 0
	v_mov_b32_e32 v73, 0
	v_mov_b32_e32 v74, 0
	v_mov_b32_e32 v75, 0
	v_mov_b32_e32 v76, 0
	v_mov_b32_e32 v77, 0
	v_mov_b32_e32 v78, 0
	v_mov_b32_e32 v79, 0
	v_mov_b32_e32 v80, 0
	v_mov_b32_e32 v81, 0
	v_mov_b32_e32 v82, 0
	v_mov_b32_e32 v83, 0
	v_mov_b32_e32 v84, 0
	v_mov_b32_e32 v85, 0
	v_mov_b32_e32 v86, 0
	v_mov_b32_e32 v87, 0
	v_mov_b32_e32 v88, 0
	v_mov_b32_e32 v89, 0
	v_mov_b32_e32 v90, 0
	v_mov_b32_e32 v91, 0
	v_mov_b32_e32 v92, 0
	v_mov_b32_e32 v93, 0
	v_mov_b32_e32 v94, 0
	v_mov_b32_e32 v95, 0
	s_mov_b32 s53, 0
	v_readlane_b32 s4, v235, 34
	v_readlane_b32 s5, v235, 35
	s_lshr_b32 s55, s56, 8
	s_mul_i32 s50, s55, 0xc0000
	s_bfe_u32 s63, s56, 0x30004
	s_lshl_b32 s63, s63, 9
	s_add_u32 s50, s50, s63
	s_add_u32 s50, s50, 0xb166000
	s_add_u32 s50, s50, s4
	s_addc_u32 s51, s5, 0
	s_mul_i32 s55, s55, 192
	s_lshr_b32 s4, s52, 11
	s_mul_i32 s4, s4, 96
	s_add_u32 s58, s55, s4
	s_lshr_b32 s4, s58, 12
	s_mov_b32 s59, s4
	s_mul_i32 s4, s4, 0x9000
	s_add_u32 s4, s4, s63
	s_add_u32 s4, s4, s46
	s_addc_u32 s5, s47, 0
	global_load_dwordx2 v[226:227], v169, s[4:5]
	global_load_dwordx2 v[228:229], v169, s[4:5] offset:128
	s_add_u32 s4, s58, 95
	s_lshr_b32 s4, s4, 12
	s_mul_i32 s4, s4, 0x9000
	s_add_u32 s4, s4, s63
	s_add_u32 s4, s4, s46
	s_addc_u32 s5, s47, 0
	global_load_dwordx2 v[230:231], v169, s[4:5]
	global_load_dwordx2 v[232:233], v169, s[4:5] offset:128
	s_add_u32 s4, s50, 0x0
	s_addc_u32 s5, s51, 0
	global_load_dwordx2 v[96:97], v225, s[4:5]
	global_load_dwordx2 v[98:99], v225, s[4:5] offset:128
	s_add_u32 s4, s50, 0x1000
	s_addc_u32 s5, s51, 0
	global_load_dwordx2 v[100:101], v225, s[4:5]
	global_load_dwordx2 v[102:103], v225, s[4:5] offset:128
	s_add_u32 s4, s50, 0x2000
	s_addc_u32 s5, s51, 0
	global_load_dwordx2 v[104:105], v225, s[4:5]
	global_load_dwordx2 v[106:107], v225, s[4:5] offset:128
	s_add_u32 s4, s50, 0x3000
	s_addc_u32 s5, s51, 0
	global_load_dwordx2 v[108:109], v225, s[4:5]
	global_load_dwordx2 v[110:111], v225, s[4:5] offset:128
	s_add_u32 s4, s50, 0x10000
	s_addc_u32 s5, s51, 0
	global_load_dwordx2 v[112:113], v225, s[4:5]
	global_load_dwordx2 v[114:115], v225, s[4:5] offset:128
	s_add_u32 s4, s50, 0x11000
	s_addc_u32 s5, s51, 0
	global_load_dwordx2 v[116:117], v225, s[4:5]
	global_load_dwordx2 v[118:119], v225, s[4:5] offset:128
	s_add_u32 s4, s50, 0x12000
	s_addc_u32 s5, s51, 0
	global_load_dwordx2 v[120:121], v225, s[4:5]
	global_load_dwordx2 v[122:123], v225, s[4:5] offset:128
	s_add_u32 s4, s50, 0x13000
	s_addc_u32 s5, s51, 0
	global_load_dwordx2 v[124:125], v225, s[4:5]
	global_load_dwordx2 v[126:127], v225, s[4:5] offset:128
.Lop_k:
	s_waitcnt vmcnt(0)
	s_barrier
	s_xor_b32 s57, s57, 0x4000
	s_cmp_eq_u32 s53, 15
	s_cbranch_scc1 .Lop_nob
	s_add_u32 m0, s57, 0x0
	s_add_u32 s4, s36, 0x0
	s_addc_u32 s5, s37, 0
	global_load_lds_dwordx4 v168, s[4:5]
	s_add_u32 m0, s57, 0x1000
	s_add_u32 s4, s36, 0x11000
	s_addc_u32 s5, s37, 0
	global_load_lds_dwordx4 v168, s[4:5]
	s_add_u32 m0, s57, 0x2000
	s_add_u32 s4, s36, 0x22000
	s_addc_u32 s5, s37, 0
	global_load_lds_dwordx4 v168, s[4:5]
	s_add_u32 m0, s57, 0x3000
	s_add_u32 s4, s36, 0x33000
	s_addc_u32 s5, s37, 0
	global_load_lds_dwordx4 v168, s[4:5]
	s_add_u32 s36, s36, 0x80
	s_addc_u32 s37, s37, 0
.Lop_nob:
	ds_read_b128 v[204:207], v222
	ds_read_b128 v[208:211], v222 offset:2048
	ds_read_b128 v[212:215], v222 offset:4096
	ds_read_b128 v[216:219], v222 offset:6144
	ds_read_b128 a[0:3], v223
	ds_read_b128 a[4:7], v223 offset:2048
	ds_read_b128 a[8:11], v223 offset:4096
	ds_read_b128 a[12:15], v223 offset:6144
	ds_read_b128 v[136:139], v220
	ds_read_b128 v[140:143], v220 offset:2048
	ds_read_b128 v[144:147], v220 offset:4096
	ds_read_b128 v[148:151], v220 offset:6144
	ds_read_b128 v[152:155], v220 offset:8192
	ds_read_b128 v[156:159], v220 offset:10240
	s_waitcnt lgkmcnt(5)
	v_mfma_f32_16x16x32_bf16 v[0:3], v[136:139], v[204:207], v[0:3]
	v_mfma_f32_16x16x32_bf16 v[4:7], v[136:139], v[208:211], v[4:7]
	v_mfma_f32_16x16x32_bf16 v[8:11], v[136:139], v[212:215], v[8:11]
	v_mfma_f32_16x16x32_bf16 v[12:15], v[136:139], v[216:219], v[12:15]
	ds_read_b128 v[136:139], v221
	s_waitcnt lgkmcnt(5)
	v_mfma_f32_16x16x32_bf16 v[16:19], v[140:143], v[204:207], v[16:19]
	v_mfma_f32_16x16x32_bf16 v[20:23], v[140:143], v[208:211], v[20:23]
	v_mfma_f32_16x16x32_bf16 v[24:27], v[140:143], v[212:215], v[24:27]
	v_mfma_f32_16x16x32_bf16 v[28:31], v[140:143], v[216:219], v[28:31]
	ds_read_b128 v[140:143], v221 offset:2048
	s_waitcnt lgkmcnt(5)
	v_mfma_f32_16x16x32_bf16 v[32:35], v[144:147], v[204:207], v[32:35]
	v_mfma_f32_16x16x32_bf16 v[36:39], v[144:147], v[208:211], v[36:39]
	v_mfma_f32_16x16x32_bf16 v[40:43], v[144:147], v[212:215], v[40:43]
	v_mfma_f32_16x16x32_bf16 v[44:47], v[144:147], v[216:219], v[44:47]
	ds_read_b128 v[144:147], v221 offset:4096
	s_waitcnt lgkmcnt(5)
	v_mfma_f32_16x16x32_bf16 v[48:51], v[148:151], v[204:207], v[48:51]
	v_mfma_f32_16x16x32_bf16 v[52:55], v[148:151], v[208:211], v[52:55]
	v_mfma_f32_16x16x32_bf16 v[56:59], v[148:151], v[212:215], v[56:59]
	v_mfma_f32_16x16x32_bf16 v[60:63], v[148:151], v[216:219], v[60:63]
	ds_read_b128 v[148:151], v221 offset:6144
	s_waitcnt lgkmcnt(5)
	v_mfma_f32_16x16x32_bf16 v[64:67], v[152:155], v[204:207], v[64:67]
	v_mfma_f32_16x16x32_bf16 v[68:71], v[152:155], v[208:211], v[68:71]
	v_mfma_f32_16x16x32_bf16 v[72:75], v[152:155], v[212:215], v[72:75]
	v_mfma_f32_16x16x32_bf16 v[76:79], v[152:155], v[216:219], v[76:79]
	ds_read_b128 v[152:155], v221 offset:8192
	s_waitcnt lgkmcnt(5)
	v_mfma_f32_16x16x32_bf16 v[80:83], v[156:159], v[204:207], v[80:83]
	v_mfma_f32_16x16x32_bf16 v[84:87], v[156:159], v[208:211], v[84:87]
	v_mfma_f32_16x16x32_bf16 v[88:91], v[156:159], v[212:215], v[88:91]
	v_mfma_f32_16x16x32_bf16 v[92:95], v[156:159], v[216:219], v[92:95]
	ds_read_b128 v[156:159], v221 offset:10240
	s_waitcnt lgkmcnt(0)
	s_barrier
	v_xor_b32_e32 v222, 0x4000, v222
	v_xor_b32_e32 v223, 0x4000, v223
	s_cmp_eq_u32 s53, 15
	s_cbranch_scc1 .Lop_last
	v_mfma_f32_16x16x32_bf16 v[0:3], v[136:139], a[0:3], v[0:3]
	s_add_u32 m0, s52, 0x0
	s_add_u32 s4, s34, 0x0
	s_addc_u32 s5, s35, 0
	global_load_lds_dwordx4 v224, s[4:5]
	v_mfma_f32_16x16x32_bf16 v[4:7], v[136:139], a[4:7], v[4:7]
	v_mfma_f32_16x16x32_bf16 v[8:11], v[136:139], a[8:11], v[8:11]
	s_add_u32 m0, s52, 0x1000
	s_add_u32 s4, s34, 0x11000
	s_addc_u32 s5, s35, 0
	global_load_lds_dwordx4 v224, s[4:5]
	v_mfma_f32_16x16x32_bf16 v[12:15], v[136:139], a[12:15], v[12:15]
	v_mfma_f32_16x16x32_bf16 v[16:19], v[140:143], a[0:3], v[16:19]
	s_add_u32 m0, s52, 0x2000
	s_add_u32 s4, s34, 0x22000
	s_addc_u32 s5, s35, 0
	global_load_lds_dwordx4 v224, s[4:5]
	v_mfma_f32_16x16x32_bf16 v[20:23], v[140:143], a[4:7], v[20:23]
	v_mfma_f32_16x16x32_bf16 v[24:27], v[140:143], a[8:11], v[24:27]
	s_add_u32 m0, s52, 0x3000
	s_add_u32 s4, s34, 0x33000
	s_addc_u32 s5, s35, 0
	global_load_lds_dwordx4 v224, s[4:5]
	v_mfma_f32_16x16x32_bf16 v[28:31], v[140:143], a[12:15], v[28:31]
	v_mfma_f32_16x16x32_bf16 v[32:35], v[144:147], a[0:3], v[32:35]
	s_add_u32 m0, s52, 0x4000
	s_add_u32 s4, s34, 0x44000
	s_addc_u32 s5, s35, 0
	global_load_lds_dwordx4 v224, s[4:5]
	v_mfma_f32_16x16x32_bf16 v[36:39], v[144:147], a[4:7], v[36:39]
	v_mfma_f32_16x16x32_bf16 v[40:43], v[144:147], a[8:11], v[40:43]
	s_add_u32 m0, s52, 0x5000
	s_add_u32 s4, s34, 0x55000
	s_addc_u32 s5, s35, 0
	global_load_lds_dwordx4 v224, s[4:5]
	v_mfma_f32_16x16x32_bf16 v[44:47], v[144:147], a[12:15], v[44:47]
	v_mfma_f32_16x16x32_bf16 v[48:51], v[148:151], a[0:3], v[48:51]
	v_mfma_f32_16x16x32_bf16 v[52:55], v[148:151], a[4:7], v[52:55]
	v_mfma_f32_16x16x32_bf16 v[56:59], v[148:151], a[8:11], v[56:59]
	v_mfma_f32_16x16x32_bf16 v[60:63], v[148:151], a[12:15], v[60:63]
	v_mfma_f32_16x16x32_bf16 v[64:67], v[152:155], a[0:3], v[64:67]
	v_mfma_f32_16x16x32_bf16 v[68:71], v[152:155], a[4:7], v[68:71]
	v_mfma_f32_16x16x32_bf16 v[72:75], v[152:155], a[8:11], v[72:75]
	v_mfma_f32_16x16x32_bf16 v[76:79], v[152:155], a[12:15], v[76:79]
	v_mfma_f32_16x16x32_bf16 v[80:83], v[156:159], a[0:3], v[80:83]
	v_mfma_f32_16x16x32_bf16 v[84:87], v[156:159], a[4:7], v[84:87]
	v_mfma_f32_16x16x32_bf16 v[88:91], v[156:159], a[8:11], v[88:91]
	v_mfma_f32_16x16x32_bf16 v[92:95], v[156:159], a[12:15], v[92:95]
	s_add_u32 s34, s34, 0x80
	s_addc_u32 s35, s35, 0
	s_add_u32 s53, s53, 1
	s_branch .Lop_k
.Lop_last:
	v_readlane_b32 s55, v235, 33
	s_add_u32 s54, s54, s55
	s_cmp_ge_u32 s54, 0x200
	s_cbranch_scc1 .Lop_nopf
	s_and_b32 s55, s54, 7
	s_lshl_b32 s55, s55, 3
	s_lshr_b32 s62, s54, 6
	s_add_u32 s55, s55, s62
	s_bfe_u32 s36, s54, 0x30003
	s_lshl_b32 s62, s55, 8
	s_lshl_b32 s63, s36, 4
	s_or_b32 s62, s62, s63
	v_readlane_b32 s4, v235, 34
	v_readlane_b32 s5, v235, 35
	s_mul_i32 s34, s55, 0x66000
	s_add_u32 s34, s34, 0x19ce6000
	s_add_u32 s34, s34, s4
	s_addc_u32 s35, s5, 0
	s_mul_i32 s36, s36, 0x44000
	s_add_u32 s36, s36, s44
	s_addc_u32 s37, s45, 0
	s_add_u32 m0, s52, 0x0
	s_add_u32 s4, s34, 0x0
	s_addc_u32 s5, s35, 0
	global_load_lds_dwordx4 v224, s[4:5]
	s_add_u32 m0, s52, 0x1000
	s_add_u32 s4, s34, 0x11000
	s_addc_u32 s5, s35, 0
	global_load_lds_dwordx4 v224, s[4:5]
	s_add_u32 m0, s52, 0x2000
	s_add_u32 s4, s34, 0x22000
	s_addc_u32 s5, s35, 0
	global_load_lds_dwordx4 v224, s[4:5]
	s_add_u32 m0, s52, 0x3000
	s_add_u32 s4, s34, 0x33000
	s_addc_u32 s5, s35, 0
	global_load_lds_dwordx4 v224, s[4:5]
	s_add_u32 m0, s52, 0x4000
	s_add_u32 s4, s34, 0x44000
	s_addc_u32 s5, s35, 0
	global_load_lds_dwordx4 v224, s[4:5]
	s_add_u32 m0, s52, 0x5000
	s_add_u32 s4, s34, 0x55000
	s_addc_u32 s5, s35, 0
	global_load_lds_dwordx4 v224, s[4:5]
	s_add_u32 m0, s57, 0x0
	s_add_u32 s4, s36, 0x0
	s_addc_u32 s5, s37, 0
	global_load_lds_dwordx4 v168, s[4:5]
	s_add_u32 m0, s57, 0x1000
	s_add_u32 s4, s36, 0x11000
	s_addc_u32 s5, s37, 0
	global_load_lds_dwordx4 v168, s[4:5]
	s_add_u32 m0, s57, 0x2000
	s_add_u32 s4, s36, 0x22000
	s_addc_u32 s5, s37, 0
	global_load_lds_dwordx4 v168, s[4:5]
	s_add_u32 m0, s57, 0x3000
	s_add_u32 s4, s36, 0x33000
	s_addc_u32 s5, s37, 0
	global_load_lds_dwordx4 v168, s[4:5]
	s_add_u32 s36, s36, 0x80
	s_addc_u32 s37, s37, 0
	s_add_u32 s34, s34, 0x80
	s_addc_u32 s35, s35, 0
.Lop_nopf:
	v_mfma_f32_16x16x32_bf16 v[0:3], v[136:139], a[0:3], v[0:3]
	v_mfma_f32_16x16x32_bf16 v[4:7], v[136:139], a[4:7], v[4:7]
	v_mfma_f32_16x16x32_bf16 v[8:11], v[136:139], a[8:11], v[8:11]
	v_mfma_f32_16x16x32_bf16 v[12:15], v[136:139], a[12:15], v[12:15]
	v_mfma_f32_16x16x32_bf16 v[16:19], v[140:143], a[0:3], v[16:19]
	v_mfma_f32_16x16x32_bf16 v[20:23], v[140:143], a[4:7], v[20:23]
	v_mfma_f32_16x16x32_bf16 v[24:27], v[140:143], a[8:11], v[24:27]
	v_mfma_f32_16x16x32_bf16 v[28:31], v[140:143], a[12:15], v[28:31]
	v_mfma_f32_16x16x32_bf16 v[32:35], v[144:147], a[0:3], v[32:35]
	v_mfma_f32_16x16x32_bf16 v[36:39], v[144:147], a[4:7], v[36:39]
	v_mfma_f32_16x16x32_bf16 v[40:43], v[144:147], a[8:11], v[40:43]
	v_mfma_f32_16x16x32_bf16 v[44:47], v[144:147], a[12:15], v[44:47]
	v_mfma_f32_16x16x32_bf16 v[48:51], v[148:151], a[0:3], v[48:51]
	v_mfma_f32_16x16x32_bf16 v[52:55], v[148:151], a[4:7], v[52:55]
	v_mfma_f32_16x16x32_bf16 v[56:59], v[148:151], a[8:11], v[56:59]
	v_mfma_f32_16x16x32_bf16 v[60:63], v[148:151], a[12:15], v[60:63]
	v_mfma_f32_16x16x32_bf16 v[64:67], v[152:155], a[0:3], v[64:67]
	v_mfma_f32_16x16x32_bf16 v[68:71], v[152:155], a[4:7], v[68:71]
	v_mfma_f32_16x16x32_bf16 v[72:75], v[152:155], a[8:11], v[72:75]
	v_mfma_f32_16x16x32_bf16 v[76:79], v[152:155], a[12:15], v[76:79]
	v_mfma_f32_16x16x32_bf16 v[80:83], v[156:159], a[0:3], v[80:83]
	v_mfma_f32_16x16x32_bf16 v[84:87], v[156:159], a[4:7], v[84:87]
	v_mfma_f32_16x16x32_bf16 v[88:91], v[156:159], a[8:11], v[88:91]
	v_mfma_f32_16x16x32_bf16 v[92:95], v[156:159], a[12:15], v[92:95]
	s_mov_b32 s55, 0x3fd744fd
	s_add_u32 s4, s50, 0x20000
	s_addc_u32 s5, s51, 0
	global_load_dwordx2 v[136:137], v225, s[4:5]
	global_load_dwordx2 v[138:139], v225, s[4:5] offset:128
	s_add_u32 s4, s50, 0x21000
	s_addc_u32 s5, s51, 0
	global_load_dwordx2 v[140:141], v225, s[4:5]
	global_load_dwordx2 v[142:143], v225, s[4:5] offset:128
	s_add_u32 s4, s50, 0x22000
	s_addc_u32 s5, s51, 0
	global_load_dwordx2 v[144:145], v225, s[4:5]
	global_load_dwordx2 v[146:147], v225, s[4:5] offset:128
	s_add_u32 s4, s50, 0x23000
	s_addc_u32 s5, s51, 0
	global_load_dwordx2 v[148:149], v225, s[4:5]
	global_load_dwordx2 v[150:151], v225, s[4:5] offset:128
	s_add_u32 s4, s50, 0x30000
	s_addc_u32 s5, s51, 0
	global_load_dwordx2 v[152:153], v225, s[4:5]
	global_load_dwordx2 v[154:155], v225, s[4:5] offset:128
	s_add_u32 s4, s50, 0x31000
	s_addc_u32 s5, s51, 0
	global_load_dwordx2 v[156:157], v225, s[4:5]
	global_load_dwordx2 v[158:159], v225, s[4:5] offset:128
	s_add_u32 s4, s50, 0x32000
	s_addc_u32 s5, s51, 0
	global_load_dwordx2 v[160:161], v225, s[4:5]
	global_load_dwordx2 v[162:163], v225, s[4:5] offset:128
	s_add_u32 s4, s50, 0x33000
	s_addc_u32 s5, s51, 0
	global_load_dwordx2 v[164:165], v225, s[4:5]
	global_load_dwordx2 v[166:167], v225, s[4:5] offset:128
	s_add_u32 s4, s50, 0x40000
	s_addc_u32 s5, s51, 0
	global_load_dwordx2 v[204:205], v225, s[4:5]
	global_load_dwordx2 v[206:207], v225, s[4:5] offset:128
	s_add_u32 s4, s50, 0x41000
	s_addc_u32 s5, s51, 0
	global_load_dwordx2 v[208:209], v225, s[4:5]
	global_load_dwordx2 v[210:211], v225, s[4:5] offset:128
	s_add_u32 s4, s50, 0x42000
	s_addc_u32 s5, s51, 0
	global_load_dwordx2 v[212:213], v225, s[4:5]
	global_load_dwordx2 v[214:215], v225, s[4:5] offset:128
	s_add_u32 s4, s50, 0x43000
	s_addc_u32 s5, s51, 0
	global_load_dwordx2 v[216:217], v225, s[4:5]
	global_load_dwordx2 v[218:219], v225, s[4:5] offset:128
	s_nop 7
	s_nop 7
	v_mul_f32_e32 v96, s55, v96
	v_mul_f32_e32 v97, s55, v97
	v_mul_f32_e32 v98, s55, v98
	v_mul_f32_e32 v99, s55, v99
	v_fmac_f32_e32 v96, v226, v0
	v_fmac_f32_e32 v97, v227, v4
	v_fmac_f32_e32 v98, v228, v8
	v_fmac_f32_e32 v99, v229, v12
	v_mul_f32_e32 v100, s55, v100
	v_mul_f32_e32 v101, s55, v101
	v_mul_f32_e32 v102, s55, v102
	v_mul_f32_e32 v103, s55, v103
	v_fmac_f32_e32 v100, v226, v1
	v_fmac_f32_e32 v101, v227, v5
	v_fmac_f32_e32 v102, v228, v9
	v_fmac_f32_e32 v103, v229, v13
	v_mul_f32_e32 v104, s55, v104
	v_mul_f32_e32 v105, s55, v105
	v_mul_f32_e32 v106, s55, v106
	v_mul_f32_e32 v107, s55, v107
	v_fmac_f32_e32 v104, v226, v2
	v_fmac_f32_e32 v105, v227, v6
	v_fmac_f32_e32 v106, v228, v10
	v_fmac_f32_e32 v107, v229, v14
	v_mul_f32_e32 v108, s55, v108
	v_mul_f32_e32 v109, s55, v109
	v_mul_f32_e32 v110, s55, v110
	v_mul_f32_e32 v111, s55, v111
	v_fmac_f32_e32 v108, v226, v3
	v_fmac_f32_e32 v109, v227, v7
	v_fmac_f32_e32 v110, v228, v11
	v_fmac_f32_e32 v111, v229, v15
	s_add_u32 s4, s50, 0x0
	s_addc_u32 s5, s51, 0
	global_store_dwordx2 v225, v[96:97], s[4:5]
	global_store_dwordx2 v225, v[98:99], s[4:5] offset:128
	s_add_u32 s4, s50, 0x1000
	s_addc_u32 s5, s51, 0
	global_store_dwordx2 v225, v[100:101], s[4:5]
	global_store_dwordx2 v225, v[102:103], s[4:5] offset:128
	s_add_u32 s4, s50, 0x2000
	s_addc_u32 s5, s51, 0
	global_store_dwordx2 v225, v[104:105], s[4:5]
	global_store_dwordx2 v225, v[106:107], s[4:5] offset:128
	s_add_u32 s4, s50, 0x3000
	s_addc_u32 s5, s51, 0
	global_store_dwordx2 v225, v[108:109], s[4:5]
	global_store_dwordx2 v225, v[110:111], s[4:5] offset:128
	s_add_u32 s4, s50, 0x50000
	s_addc_u32 s5, s51, 0
	global_load_dwordx2 v[96:97], v225, s[4:5]
	global_load_dwordx2 v[98:99], v225, s[4:5] offset:128
	s_add_u32 s4, s50, 0x51000
	s_addc_u32 s5, s51, 0
	global_load_dwordx2 v[100:101], v225, s[4:5]
	global_load_dwordx2 v[102:103], v225, s[4:5] offset:128
	s_add_u32 s4, s50, 0x52000
	s_addc_u32 s5, s51, 0
	global_load_dwordx2 v[104:105], v225, s[4:5]
	global_load_dwordx2 v[106:107], v225, s[4:5] offset:128
	s_add_u32 s4, s50, 0x53000
	s_addc_u32 s5, s51, 0
	global_load_dwordx2 v[108:109], v225, s[4:5]
	global_load_dwordx2 v[110:111], v225, s[4:5] offset:128
	s_add_u32 s4, s58, 16
	s_lshr_b32 s4, s4, 12
	s_cmp_eq_u32 s4, s59
	s_cbranch_scc1 .Lop_g1
	s_mov_b32 s59, s4
	v_mov_b32_e32 v226, v230
	v_mov_b32_e32 v227, v231
	v_mov_b32_e32 v228, v232
	v_mov_b32_e32 v229, v233
.Lop_g1:
	v_mul_f32_e32 v112, s55, v112
	v_mul_f32_e32 v113, s55, v113
	v_mul_f32_e32 v114, s55, v114
	v_mul_f32_e32 v115, s55, v115
	v_fmac_f32_e32 v112, v226, v16
	v_fmac_f32_e32 v113, v227, v20
	v_fmac_f32_e32 v114, v228, v24
	v_fmac_f32_e32 v115, v229, v28
	v_mul_f32_e32 v116, s55, v116
	v_mul_f32_e32 v117, s55, v117
	v_mul_f32_e32 v118, s55, v118
	v_mul_f32_e32 v119, s55, v119
	v_fmac_f32_e32 v116, v226, v17
	v_fmac_f32_e32 v117, v227, v21
	v_fmac_f32_e32 v118, v228, v25
	v_fmac_f32_e32 v119, v229, v29
	v_mul_f32_e32 v120, s55, v120
	v_mul_f32_e32 v121, s55, v121
	v_mul_f32_e32 v122, s55, v122
	v_mul_f32_e32 v123, s55, v123
	v_fmac_f32_e32 v120, v226, v18
	v_fmac_f32_e32 v121, v227, v22
	v_fmac_f32_e32 v122, v228, v26
	v_fmac_f32_e32 v123, v229, v30
	v_mul_f32_e32 v124, s55, v124
	v_mul_f32_e32 v125, s55, v125
	v_mul_f32_e32 v126, s55, v126
	v_mul_f32_e32 v127, s55, v127
	v_fmac_f32_e32 v124, v226, v19
	v_fmac_f32_e32 v125, v227, v23
	v_fmac_f32_e32 v126, v228, v27
	v_fmac_f32_e32 v127, v229, v31
	s_add_u32 s4, s50, 0x10000
	s_addc_u32 s5, s51, 0
	global_store_dwordx2 v225, v[112:113], s[4:5]
	global_store_dwordx2 v225, v[114:115], s[4:5] offset:128
	s_add_u32 s4, s50, 0x11000
	s_addc_u32 s5, s51, 0
	global_store_dwordx2 v225, v[116:117], s[4:5]
	global_store_dwordx2 v225, v[118:119], s[4:5] offset:128
	s_add_u32 s4, s50, 0x12000
	s_addc_u32 s5, s51, 0
	global_store_dwordx2 v225, v[120:121], s[4:5]
	global_store_dwordx2 v225, v[122:123], s[4:5] offset:128
	s_add_u32 s4, s50, 0x13000
	s_addc_u32 s5, s51, 0
	global_store_dwordx2 v225, v[124:125], s[4:5]
	global_store_dwordx2 v225, v[126:127], s[4:5] offset:128
	s_add_u32 s4, s58, 32
	s_lshr_b32 s4, s4, 12
	s_cmp_eq_u32 s4, s59
	s_cbranch_scc1 .Lop_g2
	s_mov_b32 s59, s4
	v_mov_b32_e32 v226, v230
	v_mov_b32_e32 v227, v231
	v_mov_b32_e32 v228, v232
	v_mov_b32_e32 v229, v233
.Lop_g2:
	s_waitcnt vmcnt(40)
	v_mul_f32_e32 v136, s55, v136
	v_mul_f32_e32 v137, s55, v137
	v_mul_f32_e32 v138, s55, v138
	v_mul_f32_e32 v139, s55, v139
	v_fmac_f32_e32 v136, v226, v32
	v_fmac_f32_e32 v137, v227, v36
	v_fmac_f32_e32 v138, v228, v40
	v_fmac_f32_e32 v139, v229, v44
	v_mul_f32_e32 v140, s55, v140
	v_mul_f32_e32 v141, s55, v141
	v_mul_f32_e32 v142, s55, v142
	v_mul_f32_e32 v143, s55, v143
	v_fmac_f32_e32 v140, v226, v33
	v_fmac_f32_e32 v141, v227, v37
	v_fmac_f32_e32 v142, v228, v41
	v_fmac_f32_e32 v143, v229, v45
	v_mul_f32_e32 v144, s55, v144
	v_mul_f32_e32 v145, s55, v145
	v_mul_f32_e32 v146, s55, v146
	v_mul_f32_e32 v147, s55, v147
	v_fmac_f32_e32 v144, v226, v34
	v_fmac_f32_e32 v145, v227, v38
	v_fmac_f32_e32 v146, v228, v42
	v_fmac_f32_e32 v147, v229, v46
	v_mul_f32_e32 v148, s55, v148
	v_mul_f32_e32 v149, s55, v149
	v_mul_f32_e32 v150, s55, v150
	v_mul_f32_e32 v151, s55, v151
	v_fmac_f32_e32 v148, v226, v35
	v_fmac_f32_e32 v149, v227, v39
	v_fmac_f32_e32 v150, v228, v43
	v_fmac_f32_e32 v151, v229, v47
	s_add_u32 s4, s50, 0x20000
	s_addc_u32 s5, s51, 0
	global_store_dwordx2 v225, v[136:137], s[4:5]
	global_store_dwordx2 v225, v[138:139], s[4:5] offset:128
	s_add_u32 s4, s50, 0x21000
	s_addc_u32 s5, s51, 0
	global_store_dwordx2 v225, v[140:141], s[4:5]
	global_store_dwordx2 v225, v[142:143], s[4:5] offset:128
	s_add_u32 s4, s50, 0x22000
	s_addc_u32 s5, s51, 0
	global_store_dwordx2 v225, v[144:145], s[4:5]
	global_store_dwordx2 v225, v[146:147], s[4:5] offset:128
	s_add_u32 s4, s50, 0x23000
	s_addc_u32 s5, s51, 0
	global_store_dwordx2 v225, v[148:149], s[4:5]
	global_store_dwordx2 v225, v[150:151], s[4:5] offset:128
	s_add_u32 s4, s58, 48
	s_lshr_b32 s4, s4, 12
	s_cmp_eq_u32 s4, s59
	s_cbranch_scc1 .Lop_g3
	s_mov_b32 s59, s4
	v_mov_b32_e32 v226, v230
	v_mov_b32_e32 v227, v231
	v_mov_b32_e32 v228, v232
	v_mov_b32_e32 v229, v233
.Lop_g3:
	s_waitcnt vmcnt(40)
	v_mul_f32_e32 v152, s55, v152
	v_mul_f32_e32 v153, s55, v153
	v_mul_f32_e32 v154, s55, v154
	v_mul_f32_e32 v155, s55, v155
	v_fmac_f32_e32 v152, v226, v48
	v_fmac_f32_e32 v153, v227, v52
	v_fmac_f32_e32 v154, v228, v56
	v_fmac_f32_e32 v155, v229, v60
	v_mul_f32_e32 v156, s55, v156
	v_mul_f32_e32 v157, s55, v157
	v_mul_f32_e32 v158, s55, v158
	v_mul_f32_e32 v159, s55, v159
	v_fmac_f32_e32 v156, v226, v49
	v_fmac_f32_e32 v157, v227, v53
	v_fmac_f32_e32 v158, v228, v57
	v_fmac_f32_e32 v159, v229, v61
	v_mul_f32_e32 v160, s55, v160
	v_mul_f32_e32 v161, s55, v161
	v_mul_f32_e32 v162, s55, v162
	v_mul_f32_e32 v163, s55, v163
	v_fmac_f32_e32 v160, v226, v50
	v_fmac_f32_e32 v161, v227, v54
	v_fmac_f32_e32 v162, v228, v58
	v_fmac_f32_e32 v163, v229, v62
	v_mul_f32_e32 v164, s55, v164
	v_mul_f32_e32 v165, s55, v165
	v_mul_f32_e32 v166, s55, v166
	v_mul_f32_e32 v167, s55, v167
	v_fmac_f32_e32 v164, v226, v51
	v_fmac_f32_e32 v165, v227, v55
	v_fmac_f32_e32 v166, v228, v59
	v_fmac_f32_e32 v167, v229, v63
	s_add_u32 s4, s50, 0x30000
	s_addc_u32 s5, s51, 0
	global_store_dwordx2 v225, v[152:153], s[4:5]
	global_store_dwordx2 v225, v[154:155], s[4:5] offset:128
	s_add_u32 s4, s50, 0x31000
	s_addc_u32 s5, s51, 0
	global_store_dwordx2 v225, v[156:157], s[4:5]
	global_store_dwordx2 v225, v[158:159], s[4:5] offset:128
	s_add_u32 s4, s50, 0x32000
	s_addc_u32 s5, s51, 0
	global_store_dwordx2 v225, v[160:161], s[4:5]
	global_store_dwordx2 v225, v[162:163], s[4:5] offset:128
	s_add_u32 s4, s50, 0x33000
	s_addc_u32 s5, s51, 0
	global_store_dwordx2 v225, v[164:165], s[4:5]
	global_store_dwordx2 v225, v[166:167], s[4:5] offset:128
	s_add_u32 s4, s58, 64
	s_lshr_b32 s4, s4, 12
	s_cmp_eq_u32 s4, s59
	s_cbranch_scc1 .Lop_g4
	s_mov_b32 s59, s4
	v_mov_b32_e32 v226, v230
	v_mov_b32_e32 v227, v231
	v_mov_b32_e32 v228, v232
	v_mov_b32_e32 v229, v233
.Lop_g4:
	s_waitcnt vmcnt(40)
	v_mul_f32_e32 v204, s55, v204
	v_mul_f32_e32 v205, s55, v205
	v_mul_f32_e32 v206, s55, v206
	v_mul_f32_e32 v207, s55, v207
	v_fmac_f32_e32 v204, v226, v64
	v_fmac_f32_e32 v205, v227, v68
	v_fmac_f32_e32 v206, v228, v72
	v_fmac_f32_e32 v207, v229, v76
	v_mul_f32_e32 v208, s55, v208
	v_mul_f32_e32 v209, s55, v209
	v_mul_f32_e32 v210, s55, v210
	v_mul_f32_e32 v211, s55, v211
	v_fmac_f32_e32 v208, v226, v65
	v_fmac_f32_e32 v209, v227, v69
	v_fmac_f32_e32 v210, v228, v73
	v_fmac_f32_e32 v211, v229, v77
	v_mul_f32_e32 v212, s55, v212
	v_mul_f32_e32 v213, s55, v213
	v_mul_f32_e32 v214, s55, v214
	v_mul_f32_e32 v215, s55, v215
	v_fmac_f32_e32 v212, v226, v66
	v_fmac_f32_e32 v213, v227, v70
	v_fmac_f32_e32 v214, v228, v74
	v_fmac_f32_e32 v215, v229, v78
	v_mul_f32_e32 v216, s55, v216
	v_mul_f32_e32 v217, s55, v217
	v_mul_f32_e32 v218, s55, v218
	v_mul_f32_e32 v219, s55, v219
	v_fmac_f32_e32 v216, v226, v67
	v_fmac_f32_e32 v217, v227, v71
	v_fmac_f32_e32 v218, v228, v75
	v_fmac_f32_e32 v219, v229, v79
	s_add_u32 s4, s50, 0x40000
	s_addc_u32 s5, s51, 0
	global_store_dwordx2 v225, v[204:205], s[4:5]
	global_store_dwordx2 v225, v[206:207], s[4:5] offset:128
	s_add_u32 s4, s50, 0x41000
	s_addc_u32 s5, s51, 0
	global_store_dwordx2 v225, v[208:209], s[4:5]
	global_store_dwordx2 v225, v[210:211], s[4:5] offset:128
	s_add_u32 s4, s50, 0x42000
	s_addc_u32 s5, s51, 0
	global_store_dwordx2 v225, v[212:213], s[4:5]
	global_store_dwordx2 v225, v[214:215], s[4:5] offset:128
	s_add_u32 s4, s50, 0x43000
	s_addc_u32 s5, s51, 0
	global_store_dwordx2 v225, v[216:217], s[4:5]
	global_store_dwordx2 v225, v[218:219], s[4:5] offset:128
	s_add_u32 s4, s58, 80
	s_lshr_b32 s4, s4, 12
	s_cmp_eq_u32 s4, s59
	s_cbranch_scc1 .Lop_g5
	s_mov_b32 s59, s4
	v_mov_b32_e32 v226, v230
	v_mov_b32_e32 v227, v231
	v_mov_b32_e32 v228, v232
	v_mov_b32_e32 v229, v233
.Lop_g5:
	s_waitcnt vmcnt(32)
	v_mul_f32_e32 v96, s55, v96
	v_mul_f32_e32 v97, s55, v97
	v_mul_f32_e32 v98, s55, v98
	v_mul_f32_e32 v99, s55, v99
	v_fmac_f32_e32 v96, v226, v80
	v_fmac_f32_e32 v97, v227, v84
	v_fmac_f32_e32 v98, v228, v88
	v_fmac_f32_e32 v99, v229, v92
	v_mul_f32_e32 v100, s55, v100
	v_mul_f32_e32 v101, s55, v101
	v_mul_f32_e32 v102, s55, v102
	v_mul_f32_e32 v103, s55, v103
	v_fmac_f32_e32 v100, v226, v81
	v_fmac_f32_e32 v101, v227, v85
	v_fmac_f32_e32 v102, v228, v89
	v_fmac_f32_e32 v103, v229, v93
	v_mul_f32_e32 v104, s55, v104
	v_mul_f32_e32 v105, s55, v105
	v_mul_f32_e32 v106, s55, v106
	v_mul_f32_e32 v107, s55, v107
	v_fmac_f32_e32 v104, v226, v82
	v_fmac_f32_e32 v105, v227, v86
	v_fmac_f32_e32 v106, v228, v90
	v_fmac_f32_e32 v107, v229, v94
	v_mul_f32_e32 v108, s55, v108
	v_mul_f32_e32 v109, s55, v109
	v_mul_f32_e32 v110, s55, v110
	v_mul_f32_e32 v111, s55, v111
	v_fmac_f32_e32 v108, v226, v83
	v_fmac_f32_e32 v109, v227, v87
	v_fmac_f32_e32 v110, v228, v91
	v_fmac_f32_e32 v111, v229, v95
	s_add_u32 s4, s50, 0x50000
	s_addc_u32 s5, s51, 0
	global_store_dwordx2 v225, v[96:97], s[4:5]
	global_store_dwordx2 v225, v[98:99], s[4:5] offset:128
	s_add_u32 s4, s50, 0x51000
	s_addc_u32 s5, s51, 0
	global_store_dwordx2 v225, v[100:101], s[4:5]
	global_store_dwordx2 v225, v[102:103], s[4:5] offset:128
	s_add_u32 s4, s50, 0x52000
	s_addc_u32 s5, s51, 0
	global_store_dwordx2 v225, v[104:105], s[4:5]
	global_store_dwordx2 v225, v[106:107], s[4:5] offset:128
	s_add_u32 s4, s50, 0x53000
	s_addc_u32 s5, s51, 0
	global_store_dwordx2 v225, v[108:109], s[4:5]
	global_store_dwordx2 v225, v[110:111], s[4:5] offset:128
	s_cmp_ge_u32 s54, 0x200
	s_cbranch_scc1 .Lop_done
	s_branch .Lop_tile

.LBB0_1204:
	v_add_u32_e32 v80, 0x1000, v144
	v_add_u32_e32 v131, 0x2000, v144
	v_lshrrev_b32_e32 v80, 12, v80
	s_movk_i32 s4, 0xfff
	v_add_u32_e32 v80, 1, v80
	v_cmp_lt_i32_e32 vcc, s4, v131
	v_mov_b64_e32 v[82:83], s[44:45]
	global_load_dwordx4 v[112:115], v[148:149], off offset:-2048
	global_load_dwordx4 v[108:111], v[148:149], off offset:-1024
	global_load_dwordx4 v[104:107], v[148:149], off
	global_load_dwordx4 v[100:103], v[148:149], off offset:1024
	v_cndmask_b32_e32 v128, 0, v80, vcc
	v_lshl_add_u64 v[80:81], v[128:129], 0, s[40:41]
	v_mad_u64_u32 v[82:83], s[34:35], v80, s84, v[82:83]
	v_mad_i32_i24 v83, v81, s84, v83
	v_lshlrev_b32_e32 v128, 2, v136
	v_lshl_add_u64 v[80:81], v[82:83], 0, v[128:129]
	s_waitcnt vmcnt(12)
	v_add_co_u32_e32 v86, vcc, 0x1000, v80
	v_lshl_add_u64 v[84:85], v[80:81], 0, s[48:49]
	s_nop 0
	v_addc_co_u32_e32 v87, vcc, 0, v81, vcc
	global_load_dwordx4 v[96:99], v[80:81], off
	global_load_dwordx4 v[92:95], v[80:81], off offset:1024
	global_load_dwordx4 v[120:123], v[84:85], off offset:1024
	global_load_dwordx4 v[116:119], v[84:85], off offset:2048
	global_load_dwordx4 v[88:91], v[80:81], off offset:2048
	s_nop 0
	global_load_dwordx4 v[80:83], v[80:81], off offset:3072
	s_nop 0
	global_load_dwordx4 v[124:127], v[86:87], off
	s_nop 0
	global_load_dwordx4 v[84:87], v[84:85], off offset:3072
	s_movk_i32 s4, 0x7fff
	v_cmp_lt_i32_e32 vcc, s4, v131
	s_and_saveexec_b64 s[34:35], vcc
	s_cbranch_execz .LBB0_1206
	v_mov_b32_e32 v145, v129
	v_lshlrev_b64 v[150:151], 12, v[144:145]
	v_lshl_add_u64 v[154:155], v[140:141], 0, v[150:151]
	global_load_dwordx4 v[150:153], v[154:155], off
	s_waitcnt vmcnt(0)
	v_pk_add_f32 v[112:113], v[112:113], v[150:151]
	v_pk_add_f32 v[114:115], v[114:115], v[152:153]
	global_load_dwordx4 v[150:153], v[154:155], off offset:1024
	s_waitcnt vmcnt(0)
	v_pk_add_f32 v[108:109], v[108:109], v[150:151]
	v_pk_add_f32 v[110:111], v[110:111], v[152:153]
	global_load_dwordx4 v[150:153], v[154:155], off offset:2048
	s_waitcnt vmcnt(0)
	v_pk_add_f32 v[104:105], v[104:105], v[150:151]
	v_pk_add_f32 v[106:107], v[106:107], v[152:153]
	global_load_dwordx4 v[150:153], v[154:155], off offset:3072
	s_waitcnt vmcnt(0)
	v_pk_add_f32 v[100:101], v[100:101], v[150:151]
	v_pk_add_f32 v[102:103], v[102:103], v[152:153]
.LBB0_1206:
	s_or_b64 exec, exec, s[34:35]
	v_readlane_b32 s4, v236, 21
	s_nop 1
	v_add_u32_e32 v152, s4, v144
	v_add_u32_e32 v150, 0x2000, v152
	s_movk_i32 s4, 0x3000
	v_cmp_gt_i32_e64 s[34:35], s4, v150
	v_ashrrev_i32_e32 v151, 31, v150
	s_and_saveexec_b64 s[50:51], s[34:35]
	s_cbranch_execz .LBB0_1210
	v_add_u32_e32 v32, 0x1000, v152
	v_lshrrev_b32_e32 v32, 12, v32
	s_movk_i32 s4, 0xfff
	v_add_u32_e32 v32, 1, v32
	v_cmp_lt_i32_e32 vcc, s4, v150
	v_mov_b32_e32 v33, v129
	v_mov_b64_e32 v[50:51], s[44:45]
	v_cndmask_b32_e32 v32, 0, v32, vcc
	v_lshl_add_u64 v[48:49], v[32:33], 0, s[40:41]
	v_mad_u64_u32 v[50:51], s[52:53], v48, s84, v[50:51]
	v_mad_i32_i24 v51, v49, s84, v51
	v_lshl_add_u64 v[56:57], v[50:51], 0, v[128:129]
	v_lshlrev_b64 v[32:33], 12, v[150:151]
	v_add_co_u32_e32 v74, vcc, 0x1000, v56
	v_lshl_add_u64 v[44:45], v[138:139], 0, v[32:33]
	v_lshl_add_u64 v[72:73], v[56:57], 0, s[48:49]
	v_addc_co_u32_e32 v75, vcc, 0, v57, vcc
	global_load_dwordx4 v[32:35], v[44:45], off
	global_load_dwordx4 v[36:39], v[44:45], off offset:1024
	global_load_dwordx4 v[40:43], v[44:45], off offset:2048
	s_nop 0
	global_load_dwordx4 v[44:47], v[44:45], off offset:3072
	s_nop 0
	global_load_dwordx4 v[48:51], v[56:57], off
	global_load_dwordx4 v[52:55], v[56:57], off offset:1024
	global_load_dwordx4 v[64:67], v[72:73], off offset:1024
	global_load_dwordx4 v[68:71], v[72:73], off offset:2048
	global_load_dwordx4 v[60:63], v[56:57], off offset:2048
	s_nop 0
	global_load_dwordx4 v[56:59], v[56:57], off offset:3072
	s_nop 0
	global_load_dwordx4 v[76:79], v[74:75], off
	s_nop 0
	global_load_dwordx4 v[72:75], v[72:73], off offset:3072
	s_movk_i32 s4, 0x7fff
	v_cmp_lt_i32_e32 vcc, s4, v150
	s_and_saveexec_b64 s[52:53], vcc
	s_cbranch_execz .LBB0_1209
	v_mov_b32_e32 v153, v129
	v_lshlrev_b64 v[152:153], 12, v[152:153]
	v_lshl_add_u64 v[156:157], v[140:141], 0, v[152:153]
	global_load_dwordx4 v[152:155], v[156:157], off
	s_waitcnt vmcnt(0)
	v_pk_add_f32 v[32:33], v[32:33], v[152:153]
	v_pk_add_f32 v[34:35], v[34:35], v[154:155]
	global_load_dwordx4 v[152:155], v[156:157], off offset:1024
	s_waitcnt vmcnt(0)
	v_pk_add_f32 v[36:37], v[36:37], v[152:153]
	v_pk_add_f32 v[38:39], v[38:39], v[154:155]
	global_load_dwordx4 v[152:155], v[156:157], off offset:2048
	s_waitcnt vmcnt(0)
	v_pk_add_f32 v[40:41], v[40:41], v[152:153]
	v_pk_add_f32 v[42:43], v[42:43], v[154:155]
	global_load_dwordx4 v[152:155], v[156:157], off offset:3072
	s_waitcnt vmcnt(0)
	v_pk_add_f32 v[44:45], v[44:45], v[152:153]
	v_pk_add_f32 v[46:47], v[46:47], v[154:155]

.Lfo_entry:
	v_readlane_b32 s4, v235, 34
	v_readlane_b32 s5, v235, 35
	v_readlane_b32 s55, v235, 44
	s_lshl_b32 s53, s55, 1
	s_cmp_lg_u32 s2, 1
	s_cselect_b32 s54, 1, 0
	s_add_u32 s53, s53, s54
	s_mul_i32 s53, s53, 0x5a0000
	s_add_u32 s53, s53, 0x5d88000
	s_add_u32 s44, s4, s53
	s_addc_u32 s45, s5, 0
	s_mul_i32 s54, s54, 0x6000
	s_mul_i32 s53, s55, 0x1b000
	s_add_u32 s53, s53, 0xb0fa000
	s_add_u32 s53, s53, s54
	s_add_u32 s46, s4, s53
	s_addc_u32 s47, s5, 0
	v_and_b32_e32 v225, 63, v170
	v_lshrrev_b32_e32 v226, 6, v170
	v_lshrrev_b32_e32 v227, 1, v226
	v_and_b32_e32 v228, 1, v226
	v_and_b32_e32 v229, 15, v225
	v_lshrrev_b32_e32 v230, 4, v225
	v_lshlrev_b32_e32 v231, 10, v226
	v_lshrrev_b32_e32 v232, 3, v170
	v_readfirstlane_b32 s52, v231
	v_and_b32_e32 v233, 7, v170
	v_bfe_u32 v224, v232, 1, 3
	v_xor_b32_e32 v233, v233, v224
	v_lshlrev_b32_e32 v233, 4, v233
	s_movk_i32 s4, 0x1680
	v_mad_u32_u24 v224, v232, s4, v233
	v_and_b32_e32 v233, 15, v232
	v_lshlrev_b32_e32 v233, 1, v233
	v_lshrrev_b32_e32 v168, 4, v232
	v_add_u32_e32 v233, v233, v168
	v_and_b32_e32 v168, 7, v170
	v_bfe_u32 v169, v232, 1, 3
	v_xor_b32_e32 v168, v168, v169
	v_lshlrev_b32_e32 v168, 4, v168
	v_mad_u32_u24 v168, v233, s4, v168
	v_bfe_u32 v233, v229, 1, 3
	v_xor_b32_e32 v231, v230, v233
	v_or_b32_e32 v232, 4, v230
	v_xor_b32_e32 v232, v232, v233
	v_lshlrev_b32_e32 v231, 4, v231
	v_lshlrev_b32_e32 v232, 4, v232
	s_movk_i32 s4, 96
	v_mad_u32_u24 v233, v227, s4, v229
	v_lshlrev_b32_e32 v233, 7, v233
	v_add_u32_e32 v220, v233, v231
	v_add_u32_e32 v221, v233, v232
	v_lshl_add_u32 v233, v228, 6, v229
	v_lshlrev_b32_e32 v233, 7, v233
	v_add_u32_e32 v233, 0x8000, v233
	v_add_u32_e32 v222, v233, v231
	v_add_u32_e32 v223, v233, v232
	v_lshlrev_b32_e32 v231, 2, v230
	v_mad_u32_u24 v231, v227, s4, v231
	v_lshlrev_b32_e32 v232, 5, v228
	v_add_u32_e32 v232, v232, v229
	v_lshlrev_b32_e32 v232, 1, v232
	v_lshlrev_b32_e32 v169, 2, v232
	v_lshl_add_u32 v225, v231, 12, v169
	v_readlane_b32 s54, v237, 0
	s_cmp_ge_u32 s54, 0x200
	s_cbranch_scc1 .Lfo_done
	s_add_u32 s57, s52, 0x8000
	s_and_b32 s55, s54, 7
	s_lshl_b32 s55, s55, 3
	s_lshr_b32 s62, s54, 6
	s_add_u32 s55, s55, s62
	s_bfe_u32 s36, s54, 0x30003
	s_lshl_b32 s62, s55, 8
	s_lshl_b32 s63, s36, 4
	s_or_b32 s62, s62, s63
	v_readlane_b32 s4, v235, 34
	v_readlane_b32 s5, v235, 35
	s_mul_i32 s34, s55, 0x10e000
	s_add_u32 s34, s34, 0xfae6000
	s_add_u32 s34, s34, s4
	s_addc_u32 s35, s5, 0
	s_mul_i32 s36, s36, 0xb4000
	s_add_u32 s36, s36, s44
	s_addc_u32 s37, s45, 0
	s_add_u32 m0, s52, 0x0
	s_add_u32 s4, s34, 0x0
	s_addc_u32 s5, s35, 0
	global_load_lds_dwordx4 v224, s[4:5]
	s_add_u32 m0, s52, 0x1000
	s_add_u32 s4, s34, 0x2d000
	s_addc_u32 s5, s35, 0
	global_load_lds_dwordx4 v224, s[4:5]
	s_add_u32 m0, s52, 0x2000
	s_add_u32 s4, s34, 0x5a000
	s_addc_u32 s5, s35, 0
	global_load_lds_dwordx4 v224, s[4:5]
	s_add_u32 m0, s52, 0x3000
	s_add_u32 s4, s34, 0x87000
	s_addc_u32 s5, s35, 0
	global_load_lds_dwordx4 v224, s[4:5]
	s_add_u32 m0, s52, 0x4000
	s_add_u32 s4, s34, 0xb4000
	s_addc_u32 s5, s35, 0
	global_load_lds_dwordx4 v224, s[4:5]
	s_add_u32 m0, s52, 0x5000
	s_add_u32 s4, s34, 0xe1000
	s_addc_u32 s5, s35, 0
	global_load_lds_dwordx4 v224, s[4:5]
	s_add_u32 m0, s57, 0x0
	s_add_u32 s4, s36, 0x0
	s_addc_u32 s5, s37, 0
	global_load_lds_dwordx4 v168, s[4:5]
	s_add_u32 m0, s57, 0x1000
	s_add_u32 s4, s36, 0x2d000
	s_addc_u32 s5, s37, 0
	global_load_lds_dwordx4 v168, s[4:5]
	s_add_u32 m0, s57, 0x2000
	s_add_u32 s4, s36, 0x5a000
	s_addc_u32 s5, s37, 0
	global_load_lds_dwordx4 v168, s[4:5]
	s_add_u32 m0, s57, 0x3000
	s_add_u32 s4, s36, 0x87000
	s_addc_u32 s5, s37, 0
	global_load_lds_dwordx4 v168, s[4:5]
	s_add_u32 s36, s36, 0x80
	s_addc_u32 s37, s37, 0
	s_add_u32 s34, s34, 0x80
	s_addc_u32 s35, s35, 0

.Lfo_k:
	s_waitcnt vmcnt(0)
	s_barrier
	s_xor_b32 s57, s57, 0x4000
	s_cmp_eq_u32 s53, 43
	s_cbranch_scc1 .Lfo_nob
	s_add_u32 m0, s57, 0x0
	s_add_u32 s4, s36, 0x0
	s_addc_u32 s5, s37, 0
	global_load_lds_dwordx4 v168, s[4:5]
	s_add_u32 m0, s57, 0x1000
	s_add_u32 s4, s36, 0x2d000
	s_addc_u32 s5, s37, 0
	global_load_lds_dwordx4 v168, s[4:5]
	s_add_u32 m0, s57, 0x2000
	s_add_u32 s4, s36, 0x5a000
	s_addc_u32 s5, s37, 0
	global_load_lds_dwordx4 v168, s[4:5]
	s_add_u32 m0, s57, 0x3000
	s_add_u32 s4, s36, 0x87000
	s_addc_u32 s5, s37, 0
	global_load_lds_dwordx4 v168, s[4:5]
	s_add_u32 s36, s36, 0x80
	s_addc_u32 s37, s37, 0
.Lfo_nob:
	ds_read_b128 v[204:207], v222
	ds_read_b128 v[208:211], v222 offset:2048
	ds_read_b128 v[212:215], v222 offset:4096
	ds_read_b128 v[216:219], v222 offset:6144
	ds_read_b128 a[0:3], v223
	ds_read_b128 a[4:7], v223 offset:2048
	ds_read_b128 a[8:11], v223 offset:4096
	ds_read_b128 a[12:15], v223 offset:6144
	ds_read_b128 v[136:139], v220
	ds_read_b128 v[140:143], v220 offset:2048
	ds_read_b128 v[144:147], v220 offset:4096
	ds_read_b128 v[148:151], v220 offset:6144
	ds_read_b128 v[152:155], v220 offset:8192
	ds_read_b128 v[156:159], v220 offset:10240
	s_waitcnt lgkmcnt(5)
	v_mfma_f32_16x16x32_bf16 v[0:3], v[136:139], v[204:207], v[0:3]
	v_mfma_f32_16x16x32_bf16 v[4:7], v[136:139], v[208:211], v[4:7]
	v_mfma_f32_16x16x32_bf16 v[8:11], v[136:139], v[212:215], v[8:11]
	v_mfma_f32_16x16x32_bf16 v[12:15], v[136:139], v[216:219], v[12:15]
	ds_read_b128 v[136:139], v221
	s_waitcnt lgkmcnt(5)
	v_mfma_f32_16x16x32_bf16 v[16:19], v[140:143], v[204:207], v[16:19]
	v_mfma_f32_16x16x32_bf16 v[20:23], v[140:143], v[208:211], v[20:23]
	v_mfma_f32_16x16x32_bf16 v[24:27], v[140:143], v[212:215], v[24:27]
	v_mfma_f32_16x16x32_bf16 v[28:31], v[140:143], v[216:219], v[28:31]
	ds_read_b128 v[140:143], v221 offset:2048
	s_waitcnt lgkmcnt(5)
	v_mfma_f32_16x16x32_bf16 v[32:35], v[144:147], v[204:207], v[32:35]
	v_mfma_f32_16x16x32_bf16 v[36:39], v[144:147], v[208:211], v[36:39]
	v_mfma_f32_16x16x32_bf16 v[40:43], v[144:147], v[212:215], v[40:43]
	v_mfma_f32_16x16x32_bf16 v[44:47], v[144:147], v[216:219], v[44:47]
	ds_read_b128 v[144:147], v221 offset:4096
	s_waitcnt lgkmcnt(5)
	v_mfma_f32_16x16x32_bf16 v[48:51], v[148:151], v[204:207], v[48:51]
	v_mfma_f32_16x16x32_bf16 v[52:55], v[148:151], v[208:211], v[52:55]
	v_mfma_f32_16x16x32_bf16 v[56:59], v[148:151], v[212:215], v[56:59]
	v_mfma_f32_16x16x32_bf16 v[60:63], v[148:151], v[216:219], v[60:63]
	ds_read_b128 v[148:151], v221 offset:6144
	s_waitcnt lgkmcnt(5)
	v_mfma_f32_16x16x32_bf16 v[64:67], v[152:155], v[204:207], v[64:67]
	v_mfma_f32_16x16x32_bf16 v[68:71], v[152:155], v[208:211], v[68:71]
	v_mfma_f32_16x16x32_bf16 v[72:75], v[152:155], v[212:215], v[72:75]
	v_mfma_f32_16x16x32_bf16 v[76:79], v[152:155], v[216:219], v[76:79]
	ds_read_b128 v[152:155], v221 offset:8192
	s_waitcnt lgkmcnt(5)
	v_mfma_f32_16x16x32_bf16 v[80:83], v[156:159], v[204:207], v[80:83]
	v_mfma_f32_16x16x32_bf16 v[84:87], v[156:159], v[208:211], v[84:87]
	v_mfma_f32_16x16x32_bf16 v[88:91], v[156:159], v[212:215], v[88:91]
	v_mfma_f32_16x16x32_bf16 v[92:95], v[156:159], v[216:219], v[92:95]
	ds_read_b128 v[156:159], v221 offset:10240
	s_waitcnt lgkmcnt(0)
	s_barrier
	v_xor_b32_e32 v222, 0x4000, v222
	v_xor_b32_e32 v223, 0x4000, v223
	s_cmp_eq_u32 s53, 43
	s_cbranch_scc1 .Lfo_last
	v_mfma_f32_16x16x32_bf16 v[0:3], v[136:139], a[0:3], v[0:3]
	s_add_u32 m0, s52, 0x0
	s_add_u32 s4, s34, 0x0
	s_addc_u32 s5, s35, 0
	global_load_lds_dwordx4 v224, s[4:5]
	v_mfma_f32_16x16x32_bf16 v[4:7], v[136:139], a[4:7], v[4:7]
	v_mfma_f32_16x16x32_bf16 v[8:11], v[136:139], a[8:11], v[8:11]
	s_add_u32 m0, s52, 0x1000
	s_add_u32 s4, s34, 0x2d000
	s_addc_u32 s5, s35, 0
	global_load_lds_dwordx4 v224, s[4:5]
	v_mfma_f32_16x16x32_bf16 v[12:15], v[136:139], a[12:15], v[12:15]
	v_mfma_f32_16x16x32_bf16 v[16:19], v[140:143], a[0:3], v[16:19]
	s_add_u32 m0, s52, 0x2000
	s_add_u32 s4, s34, 0x5a000
	s_addc_u32 s5, s35, 0
	global_load_lds_dwordx4 v224, s[4:5]
	v_mfma_f32_16x16x32_bf16 v[20:23], v[140:143], a[4:7], v[20:23]
	v_mfma_f32_16x16x32_bf16 v[24:27], v[140:143], a[8:11], v[24:27]
	s_add_u32 m0, s52, 0x3000
	s_add_u32 s4, s34, 0x87000
	s_addc_u32 s5, s35, 0
	global_load_lds_dwordx4 v224, s[4:5]
	v_mfma_f32_16x16x32_bf16 v[28:31], v[140:143], a[12:15], v[28:31]
	v_mfma_f32_16x16x32_bf16 v[32:35], v[144:147], a[0:3], v[32:35]
	s_add_u32 m0, s52, 0x4000
	s_add_u32 s4, s34, 0xb4000
	s_addc_u32 s5, s35, 0
	global_load_lds_dwordx4 v224, s[4:5]
	v_mfma_f32_16x16x32_bf16 v[36:39], v[144:147], a[4:7], v[36:39]
	v_mfma_f32_16x16x32_bf16 v[40:43], v[144:147], a[8:11], v[40:43]
	s_add_u32 m0, s52, 0x5000
	s_add_u32 s4, s34, 0xe1000
	s_addc_u32 s5, s35, 0
	global_load_lds_dwordx4 v224, s[4:5]
	v_mfma_f32_16x16x32_bf16 v[44:47], v[144:147], a[12:15], v[44:47]
	v_mfma_f32_16x16x32_bf16 v[48:51], v[148:151], a[0:3], v[48:51]
	v_mfma_f32_16x16x32_bf16 v[52:55], v[148:151], a[4:7], v[52:55]
	v_mfma_f32_16x16x32_bf16 v[56:59], v[148:151], a[8:11], v[56:59]
	v_mfma_f32_16x16x32_bf16 v[60:63], v[148:151], a[12:15], v[60:63]
	v_mfma_f32_16x16x32_bf16 v[64:67], v[152:155], a[0:3], v[64:67]
	v_mfma_f32_16x16x32_bf16 v[68:71], v[152:155], a[4:7], v[68:71]
	v_mfma_f32_16x16x32_bf16 v[72:75], v[152:155], a[8:11], v[72:75]
	v_mfma_f32_16x16x32_bf16 v[76:79], v[152:155], a[12:15], v[76:79]
	v_mfma_f32_16x16x32_bf16 v[80:83], v[156:159], a[0:3], v[80:83]
	v_mfma_f32_16x16x32_bf16 v[84:87], v[156:159], a[4:7], v[84:87]
	v_mfma_f32_16x16x32_bf16 v[88:91], v[156:159], a[8:11], v[88:91]
	v_mfma_f32_16x16x32_bf16 v[92:95], v[156:159], a[12:15], v[92:95]
	s_add_u32 s34, s34, 0x80
	s_addc_u32 s35, s35, 0
	s_add_u32 s53, s53, 1
	s_branch .Lfo_k
.Lfo_last:
	v_readlane_b32 s55, v235, 33
	s_add_u32 s54, s54, s55
	s_cmp_ge_u32 s54, 0x200
	s_cbranch_scc1 .Lfo_nopf
	s_and_b32 s55, s54, 7
	s_lshl_b32 s55, s55, 3
	s_lshr_b32 s62, s54, 6
	s_add_u32 s55, s55, s62
	s_bfe_u32 s36, s54, 0x30003
	s_lshl_b32 s62, s55, 8
	s_lshl_b32 s63, s36, 4
	s_or_b32 s62, s62, s63
	v_readlane_b32 s4, v235, 34
	v_readlane_b32 s5, v235, 35
	s_mul_i32 s34, s55, 0x10e000
	s_add_u32 s34, s34, 0xfae6000
	s_add_u32 s34, s34, s4
	s_addc_u32 s35, s5, 0
	s_mul_i32 s36, s36, 0xb4000
	s_add_u32 s36, s36, s44
	s_addc_u32 s37, s45, 0
	s_add_u32 m0, s52, 0x0
	s_add_u32 s4, s34, 0x0
	s_addc_u32 s5, s35, 0
	global_load_lds_dwordx4 v224, s[4:5]
	s_add_u32 m0, s52, 0x1000
	s_add_u32 s4, s34, 0x2d000
	s_addc_u32 s5, s35, 0
	global_load_lds_dwordx4 v224, s[4:5]
	s_add_u32 m0, s52, 0x2000
	s_add_u32 s4, s34, 0x5a000
	s_addc_u32 s5, s35, 0
	global_load_lds_dwordx4 v224, s[4:5]
	s_add_u32 m0, s52, 0x3000
	s_add_u32 s4, s34, 0x87000
	s_addc_u32 s5, s35, 0
	global_load_lds_dwordx4 v224, s[4:5]
	s_add_u32 m0, s52, 0x4000
	s_add_u32 s4, s34, 0xb4000
	s_addc_u32 s5, s35, 0
	global_load_lds_dwordx4 v224, s[4:5]
	s_add_u32 m0, s52, 0x5000
	s_add_u32 s4, s34, 0xe1000
	s_addc_u32 s5, s35, 0
	global_load_lds_dwordx4 v224, s[4:5]
	s_add_u32 m0, s57, 0x0
	s_add_u32 s4, s36, 0x0
	s_addc_u32 s5, s37, 0
	global_load_lds_dwordx4 v168, s[4:5]
	s_add_u32 m0, s57, 0x1000
	s_add_u32 s4, s36, 0x2d000
	s_addc_u32 s5, s37, 0
	global_load_lds_dwordx4 v168, s[4:5]
	s_add_u32 m0, s57, 0x2000
	s_add_u32 s4, s36, 0x5a000
	s_addc_u32 s5, s37, 0
	global_load_lds_dwordx4 v168, s[4:5]
	s_add_u32 m0, s57, 0x3000
	s_add_u32 s4, s36, 0x87000
	s_addc_u32 s5, s37, 0
	global_load_lds_dwordx4 v168, s[4:5]
	s_add_u32 s36, s36, 0x80
	s_addc_u32 s37, s37, 0
	s_add_u32 s34, s34, 0x80
	s_addc_u32 s35, s35, 0
.Lfo_nopf:
	v_mfma_f32_16x16x32_bf16 v[0:3], v[136:139], a[0:3], v[0:3]
	v_mfma_f32_16x16x32_bf16 v[4:7], v[136:139], a[4:7], v[4:7]
	v_mfma_f32_16x16x32_bf16 v[8:11], v[136:139], a[8:11], v[8:11]
	v_mfma_f32_16x16x32_bf16 v[12:15], v[136:139], a[12:15], v[12:15]
	v_mfma_f32_16x16x32_bf16 v[16:19], v[140:143], a[0:3], v[16:19]
	v_mfma_f32_16x16x32_bf16 v[20:23], v[140:143], a[4:7], v[20:23]
	v_mfma_f32_16x16x32_bf16 v[24:27], v[140:143], a[8:11], v[24:27]
	v_mfma_f32_16x16x32_bf16 v[28:31], v[140:143], a[12:15], v[28:31]
	v_mfma_f32_16x16x32_bf16 v[32:35], v[144:147], a[0:3], v[32:35]
	v_mfma_f32_16x16x32_bf16 v[36:39], v[144:147], a[4:7], v[36:39]
	v_mfma_f32_16x16x32_bf16 v[40:43], v[144:147], a[8:11], v[40:43]
	v_mfma_f32_16x16x32_bf16 v[44:47], v[144:147], a[12:15], v[44:47]
	v_mfma_f32_16x16x32_bf16 v[48:51], v[148:151], a[0:3], v[48:51]
	v_mfma_f32_16x16x32_bf16 v[52:55], v[148:151], a[4:7], v[52:55]
	v_mfma_f32_16x16x32_bf16 v[56:59], v[148:151], a[8:11], v[56:59]
	v_mfma_f32_16x16x32_bf16 v[60:63], v[148:151], a[12:15], v[60:63]
	v_mfma_f32_16x16x32_bf16 v[64:67], v[152:155], a[0:3], v[64:67]
	v_mfma_f32_16x16x32_bf16 v[68:71], v[152:155], a[4:7], v[68:71]
	v_mfma_f32_16x16x32_bf16 v[72:75], v[152:155], a[8:11], v[72:75]
	v_mfma_f32_16x16x32_bf16 v[76:79], v[152:155], a[12:15], v[76:79]
	v_mfma_f32_16x16x32_bf16 v[80:83], v[156:159], a[0:3], v[80:83]
	v_mfma_f32_16x16x32_bf16 v[84:87], v[156:159], a[4:7], v[84:87]
	v_mfma_f32_16x16x32_bf16 v[88:91], v[156:159], a[8:11], v[88:91]
	v_mfma_f32_16x16x32_bf16 v[92:95], v[156:159], a[12:15], v[92:95]
	s_mov_b32 s55, 0x3fd744fd
	v_mul_f32_e32 v226, 0.5, v226
	v_mul_f32_e32 v227, 0.5, v227
	v_mul_f32_e32 v228, 0.5, v228
	v_mul_f32_e32 v229, 0.5, v229
	v_mul_f32_e32 v230, 0.5, v230
	v_mul_f32_e32 v231, 0.5, v231
	v_mul_f32_e32 v232, 0.5, v232
	v_mul_f32_e32 v233, 0.5, v233
	s_add_u32 s4, s50, 0x20000
	s_addc_u32 s5, s51, 0
	global_load_dwordx2 v[136:137], v225, s[4:5]
	global_load_dwordx2 v[138:139], v225, s[4:5] offset:128
	s_add_u32 s4, s50, 0x21000
	s_addc_u32 s5, s51, 0
	global_load_dwordx2 v[140:141], v225, s[4:5]
	global_load_dwordx2 v[142:143], v225, s[4:5] offset:128
	s_add_u32 s4, s50, 0x22000
	s_addc_u32 s5, s51, 0
	global_load_dwordx2 v[144:145], v225, s[4:5]
	global_load_dwordx2 v[146:147], v225, s[4:5] offset:128
	s_add_u32 s4, s50, 0x23000
	s_addc_u32 s5, s51, 0
	global_load_dwordx2 v[148:149], v225, s[4:5]
	global_load_dwordx2 v[150:151], v225, s[4:5] offset:128
	s_add_u32 s4, s50, 0x30000
	s_addc_u32 s5, s51, 0
	global_load_dwordx2 v[152:153], v225, s[4:5]
	global_load_dwordx2 v[154:155], v225, s[4:5] offset:128
	s_add_u32 s4, s50, 0x31000
	s_addc_u32 s5, s51, 0
	global_load_dwordx2 v[156:157], v225, s[4:5]
	global_load_dwordx2 v[158:159], v225, s[4:5] offset:128
	s_add_u32 s4, s50, 0x32000
	s_addc_u32 s5, s51, 0
	global_load_dwordx2 v[160:161], v225, s[4:5]
	global_load_dwordx2 v[162:163], v225, s[4:5] offset:128
	s_add_u32 s4, s50, 0x33000
	s_addc_u32 s5, s51, 0
	global_load_dwordx2 v[164:165], v225, s[4:5]
	global_load_dwordx2 v[166:167], v225, s[4:5] offset:128
	s_add_u32 s4, s50, 0x40000
	s_addc_u32 s5, s51, 0
	global_load_dwordx2 v[204:205], v225, s[4:5]
	global_load_dwordx2 v[206:207], v225, s[4:5] offset:128
	s_add_u32 s4, s50, 0x41000
	s_addc_u32 s5, s51, 0
	global_load_dwordx2 v[208:209], v225, s[4:5]
	global_load_dwordx2 v[210:211], v225, s[4:5] offset:128
	s_add_u32 s4, s50, 0x42000
	s_addc_u32 s5, s51, 0
	global_load_dwordx2 v[212:213], v225, s[4:5]
	global_load_dwordx2 v[214:215], v225, s[4:5] offset:128
	s_add_u32 s4, s50, 0x43000
	s_addc_u32 s5, s51, 0
	global_load_dwordx2 v[216:217], v225, s[4:5]
	global_load_dwordx2 v[218:219], v225, s[4:5] offset:128
	s_nop 7
	s_nop 7
	v_mul_f32_e32 v96, s55, v96
	v_mul_f32_e32 v97, s55, v97
	v_mul_f32_e32 v98, s55, v98
	v_mul_f32_e32 v99, s55, v99
	v_fmac_f32_e32 v96, v226, v0
	v_fmac_f32_e32 v97, v227, v4
	v_fmac_f32_e32 v98, v228, v8
	v_fmac_f32_e32 v99, v229, v12
	v_mul_f32_e32 v100, s55, v100
	v_mul_f32_e32 v101, s55, v101
	v_mul_f32_e32 v102, s55, v102
	v_mul_f32_e32 v103, s55, v103
	v_fmac_f32_e32 v100, v226, v1
	v_fmac_f32_e32 v101, v227, v5
	v_fmac_f32_e32 v102, v228, v9
	v_fmac_f32_e32 v103, v229, v13
	v_mul_f32_e32 v104, s55, v104
	v_mul_f32_e32 v105, s55, v105
	v_mul_f32_e32 v106, s55, v106
	v_mul_f32_e32 v107, s55, v107
	v_fmac_f32_e32 v104, v226, v2
	v_fmac_f32_e32 v105, v227, v6
	v_fmac_f32_e32 v106, v228, v10
	v_fmac_f32_e32 v107, v229, v14
	v_mul_f32_e32 v108, s55, v108
	v_mul_f32_e32 v109, s55, v109
	v_mul_f32_e32 v110, s55, v110
	v_mul_f32_e32 v111, s55, v111
	v_fmac_f32_e32 v108, v226, v3
	v_fmac_f32_e32 v109, v227, v7
	v_fmac_f32_e32 v110, v228, v11
	v_fmac_f32_e32 v111, v229, v15
	s_add_u32 s4, s50, 0x0
	s_addc_u32 s5, s51, 0
	global_store_dwordx2 v225, v[96:97], s[4:5]
	global_store_dwordx2 v225, v[98:99], s[4:5] offset:128
	s_add_u32 s4, s50, 0x1000
	s_addc_u32 s5, s51, 0
	global_store_dwordx2 v225, v[100:101], s[4:5]
	global_store_dwordx2 v225, v[102:103], s[4:5] offset:128
	s_add_u32 s4, s50, 0x2000
	s_addc_u32 s5, s51, 0
	global_store_dwordx2 v225, v[104:105], s[4:5]
	global_store_dwordx2 v225, v[106:107], s[4:5] offset:128
	s_add_u32 s4, s50, 0x3000
	s_addc_u32 s5, s51, 0
	global_store_dwordx2 v225, v[108:109], s[4:5]
	global_store_dwordx2 v225, v[110:111], s[4:5] offset:128
	s_add_u32 s4, s50, 0x50000
	s_addc_u32 s5, s51, 0
	global_load_dwordx2 v[96:97], v225, s[4:5]
	global_load_dwordx2 v[98:99], v225, s[4:5] offset:128
	s_add_u32 s4, s50, 0x51000
	s_addc_u32 s5, s51, 0
	global_load_dwordx2 v[100:101], v225, s[4:5]
	global_load_dwordx2 v[102:103], v225, s[4:5] offset:128
	s_add_u32 s4, s50, 0x52000
	s_addc_u32 s5, s51, 0
	global_load_dwordx2 v[104:105], v225, s[4:5]
	global_load_dwordx2 v[106:107], v225, s[4:5] offset:128
	s_add_u32 s4, s50, 0x53000
	s_addc_u32 s5, s51, 0
	global_load_dwordx2 v[108:109], v225, s[4:5]
	global_load_dwordx2 v[110:111], v225, s[4:5] offset:128
	s_add_u32 s4, s58, 16
	s_lshr_b32 s4, s4, 12
	s_cmp_eq_u32 s4, s59
	s_cbranch_scc1 .Lfo_g1
	s_mov_b32 s59, s4
	v_mov_b32_e32 v226, v230
	v_mov_b32_e32 v227, v231
	v_mov_b32_e32 v228, v232
	v_mov_b32_e32 v229, v233

.Lfo_done:
	s_waitcnt vmcnt(0)
	s_branch .LBB0_1229
.LBB0_1229:
	v_readlane_b32 s4, v235, 49
	s_andn2_b64 vcc, exec, s[40:41]
	v_readlane_b32 s5, v235, 50
	s_cbranch_vccnz .LBB0_1231
	s_cmp_eq_u32 s2, 0
	s_cselect_b64 s[4:5], -1, 0
